# combined: peer_q/gemm_z A-tile loads without temp copies, gemm_z K loop software-pipelined, q-proj epilogue rope loads batched 3 steps at a time, gather u-sweep back edge at the bottom
# speedup vs baseline: 1.0051x; 1.0051x over previous
; #define GL_LOAD(KT_, S) { int kt_ = MID ? (((KT_) & 8) | (((KT_) + rot) & 7)) : (((KT_) + rot) & (KT - 1)); kt_ &= ktmask; asm volatile("" : "+s"(kt_)); GL_LD1(0, S) GL_LD1(1, S) GL_LD1(2, S) GL_LD1(3, S) }
; #define GL_STORE(BUF_, S, DOSSQ_) { const bool dossq_ = (DOSSQ_); GL_ST1(0, S, BUF_, ssq0) GL_ST1(1, S, BUF_, ssq1) GL_ST1(2, S, BUF_, ssq2) GL_ST1(3, S, BUF_, ssq3) }
;     ...
;   __syncthreads();
;   GL_LOAD(0, 0);
;   GL_LOAD(1, 1);
;   GL_STORE(0, 0, true);
;   __syncthreads();
; __device__ void phase_gemm_z(const P& p, int vb, int nvb, char* smem) {
;     ...
;   for (int li = xs ? slot : vb; li < (xs ? 33 * 12 : 264 * 12); li += (xs ? nslot : nvb)) {
;     const int mt = xs ? (li / 12) * 8 + xcd : li / 12, nt = li % 12;
;     const char* arow[4]; const bool az[4] = {false, false, false, false};
; #pragma unroll
;     for (int i = 0; i < 4; i++) arow[i] = p.ws + WS_HB + (size_t)(mt * 128 + r0 + 32 * i) * 2048;
.LBB0_62:
	s_mul_hi_i32 s0, s38, 0x2aaaaaab
	s_lshr_b32 s1, s0, 31
	s_ashr_i32 s0, s0, 1
	s_add_i32 s12, s0, s1
	s_lshl_b32 s0, s12, 3
	s_or_b32 s13, s0, s33
	s_and_b64 s[0:1], s[54:55], exec
	s_cselect_b32 s0, s13, s12
	s_mul_i32 s12, s12, 12
	s_sub_i32 s13, s38, s12
	s_lshl_b32 s39, s0, 7
	s_lshl_b32 s0, s13, 2
	s_bfe_i32 s0, s0, 0x80000
	v_mov_b32_e32 v36, v178
	s_lshl_b32 s12, s13, 7
	s_mulk_i32 s0, 0x56
	s_bfe_u32 s1, s0, 0x1000f
	v_ashrrev_i32_e32 v209, 3, v36
	s_bfe_u32 s0, s0, 0x80008
	v_add_u32_e32 v2, s12, v209
	v_add_u32_e32 v0, s39, v180
	s_add_i32 s0, s0, s1
	v_ashrrev_i32_e32 v3, 31, v2
	v_and_b32_e32 v208, 7, v36
	v_lshlrev_b64 v[2:3], 11, v[2:3]
	s_and_b32 s14, s0, 15
	v_ashrrev_i32_e32 v1, 31, v0
	v_lshl_add_u64 v[2:3], s[80:81], 0, v[2:3]
	v_lshlrev_b32_e32 v156, 4, v208
	s_barrier
	s_lshl_b32 s16, s14, 6
	v_lshlrev_b64 v[0:1], 11, v[0:1]
	s_ashr_i32 s15, s14, 31
	v_lshl_add_u64 v[162:163], v[2:3], 0, v[156:157]
	s_ashr_i32 s17, s16, 31
	v_lshl_add_u64 v[164:165], s[52:53], 0, v[0:1]
	s_lshl_b64 s[14:15], s[14:15], 7
	s_lshl_b64 s[16:17], s[16:17], 1
	v_or_b32_e32 v8, s14, v156
	v_mov_b32_e32 v9, s15
	v_lshl_add_u64 v[166:167], v[164:165], 0, s[6:7]
	v_lshl_add_u64 v[168:169], v[164:165], 0, s[8:9]
	v_lshl_add_u64 v[170:171], v[164:165], 0, s[10:11]
	v_lshl_add_u64 v[172:173], v[162:163], 0, s[6:7]
	v_lshl_add_u64 v[2:3], v[162:163], 0, s[16:17]
	v_lshl_add_u64 v[4:5], v[164:165], 0, v[8:9]
	v_lshl_add_u64 v[10:11], v[166:167], 0, v[8:9]
	v_lshl_add_u64 v[12:13], v[168:169], 0, v[8:9]
	v_lshl_add_u64 v[16:17], v[170:171], 0, v[8:9]
	v_lshl_add_u64 v[20:21], v[172:173], 0, s[16:17]
	v_lshl_add_u64 v[174:175], v[162:163], 0, s[8:9]
	global_load_dwordx4 v[0:3], v[2:3], off
	s_nop 0
	global_load_dwordx4 v[4:7], v[4:5], off
	s_nop 0
	global_load_dwordx4 v[8:11], v[10:11], off
	s_nop 0
	global_load_dwordx4 v[12:15], v[12:13], off
	s_nop 0
	global_load_dwordx4 v[16:19], v[16:17], off
	v_lshl_add_u64 v[24:25], v[174:175], 0, s[16:17]
	global_load_dwordx4 v[20:23], v[20:21], off
	v_lshl_add_u64 v[176:177], v[162:163], 0, s[10:11]
	global_load_dwordx4 v[24:27], v[24:25], off
	v_lshl_add_u64 v[28:29], v[176:177], 0, s[16:17]
	global_load_dwordx4 v[28:31], v[28:29], off
	s_add_i32 s1, s0, 1
	s_and_b32 s16, s1, 15
	s_ashr_i32 s17, s16, 31
	s_lshl_b32 s40, s16, 6
	v_mul_lo_u32 v32, v209, s20
	s_lshl_b64 s[16:17], s[16:17], 7
	s_ashr_i32 s41, s40, 31
	v_add3_u32 v213, 16, v32, v156
	v_or_b32_e32 v32, s16, v156
	v_mov_b32_e32 v33, s17
	s_lshl_b64 s[16:17], s[40:41], 1
	v_lshl_add_u64 v[34:35], v[164:165], 0, v[32:33]
	s_and_b32 s14, s0, 0xff
	s_add_i32 s0, s0, 2
	s_and_b32 s0, s0, 15
	v_mov_b32_e32 v214, v157
	v_mov_b32_e32 v215, v157
	v_mov_b32_e32 v216, v157
	v_mov_b32_e32 v217, v157
	v_bfe_u32 v210, v36, 6, 1
	v_and_b32_e32 v211, 31, v36
	v_bfe_u32 v212, v36, 5, 1
	v_mov_b32_e32 v37, v157
	v_mov_b32_e32 v38, v157
	v_mov_b32_e32 v39, v157
	v_mov_b32_e32 v40, v157
	v_mov_b32_e32 v41, v157
	v_mov_b32_e32 v42, v157
	v_mov_b32_e32 v43, v157
	v_mov_b32_e32 v44, v157
	v_mov_b32_e32 v45, v157
	v_mov_b32_e32 v46, v157
	v_mov_b32_e32 v47, v157
	v_mov_b32_e32 v48, v157
	v_mov_b32_e32 v49, v157
	v_mov_b32_e32 v50, v157
	v_mov_b32_e32 v51, v157
	v_mov_b32_e32 v52, v157
	v_mov_b32_e32 v53, v157
	v_mov_b32_e32 v54, v157
	v_mov_b32_e32 v55, v157
	v_mov_b32_e32 v56, v157
	v_mov_b32_e32 v57, v157
	v_mov_b32_e32 v58, v157
	v_mov_b32_e32 v59, v157
	v_mov_b32_e32 v60, v157
	v_mov_b32_e32 v61, v157
	v_mov_b32_e32 v62, v157
	v_mov_b32_e32 v63, v157
	v_add_u32_e32 v221, 0x1200, v213
	v_add_u32_e32 v222, 0x2400, v213
	v_add_u32_e32 v223, 0x3600, v213
	s_waitcnt vmcnt(7)
	ds_write_b128 v213, v[0:3] offset:36864
	s_waitcnt vmcnt(6)
	ds_write_b128 v213, v[4:7]
	s_waitcnt vmcnt(5)
	ds_write_b128 v213, v[8:11] offset:4608
	v_lshl_add_u64 v[0:1], v[162:163], 0, s[16:17]
	s_waitcnt vmcnt(2)
	ds_write_b128 v213, v[20:23] offset:41472
	global_load_dwordx4 v[80:83], v[34:35], off
	global_load_dwordx4 v[72:75], v[0:1], off
	v_lshl_add_u64 v[0:1], v[166:167], 0, v[32:33]
	ds_write_b128 v213, v[12:15] offset:9216
	s_waitcnt vmcnt(3)
	ds_write_b128 v213, v[24:27] offset:46080
	v_lshl_add_u64 v[2:3], v[172:173], 0, s[16:17]
	global_load_dwordx4 v[84:87], v[0:1], off
	global_load_dwordx4 v[64:67], v[2:3], off
	v_lshl_add_u64 v[0:1], v[168:169], 0, v[32:33]
	ds_write_b128 v213, v[16:19] offset:13824
	s_waitcnt vmcnt(4)
	ds_write_b128 v213, v[28:31] offset:50688
	v_lshl_add_u64 v[2:3], v[174:175], 0, s[16:17]
	global_load_dwordx4 v[88:91], v[0:1], off
	global_load_dwordx4 v[68:71], v[2:3], off
	v_lshl_add_u64 v[0:1], v[170:171], 0, v[32:33]
	v_lshl_add_u64 v[2:3], v[176:177], 0, s[16:17]
	global_load_dwordx4 v[108:111], v[0:1], off
	global_load_dwordx4 v[76:79], v[2:3], off
	s_waitcnt lgkmcnt(0)
	s_barrier
; #define GL_LOAD(KT_, S) { int kt_ = MID ? (((KT_) & 8) | (((KT_) + rot) & 7)) : (((KT_) + rot) & (KT - 1)); kt_ &= ktmask; asm volatile("" : "+s"(kt_)); GL_LD1(0, S) GL_LD1(1, S) GL_LD1(2, S) GL_LD1(3, S) }
; #define GL_STORE(BUF_, S, DOSSQ_) { const bool dossq_ = (DOSSQ_); GL_ST1(0, S, BUF_, ssq0) GL_ST1(1, S, BUF_, ssq1) GL_ST1(2, S, BUF_, ssq2) GL_ST1(3, S, BUF_, ssq3) }
; #define GL_RS(DEN_) { GL_RS1(0, ssq0, DEN_) GL_RS1(1, ssq1, DEN_) GL_RS1(2, ssq2, DEN_) GL_RS1(3, ssq3, DEN_) }
;     ...
;     GL_LOAD(2, 0);
; #pragma unroll 1
;     for (int kt = 0; kt < KT; kt += 2) {
;       if (MID && kt == 8) {
;         GL_RS(512.f);
;         __syncthreads();
; #pragma unroll
;         for (int mi = 0; mi < 2; mi++) {
;           f32x16 sv;
; #pragma unroll
;           for (int r = 0; r < 16; r++) sv[r] = rs[64 * wm + 32 * mi + (r & 3) + 8 * (r >> 2) + 4 * lh];
;           acc[mi][0] *= sv; acc[mi][1] *= sv;
;         }
;       }
;       GL_COMPUTE(0);
;       GL_STORE(1, 1, !MID || (kt + 1) < 8);
;       GL_LOAD((kt + 3 < KT ? kt + 3 : KT - 1), 1);
;       __syncthreads();
	s_ashr_i32 s1, s0, 31
	s_lshl_b64 s[16:17], s[0:1], 7
	s_lshl_b32 s0, s0, 6
	v_dot2c_f32_bf16_e32 v214, v4, v4
	v_or_b32_e32 v0, s16, v156
	v_mov_b32_e32 v1, s17
	s_ashr_i32 s1, s0, 31
	v_dot2c_f32_bf16_e32 v215, v8, v8
	v_dot2c_f32_bf16_e32 v214, v5, v5
	s_lshl_b64 s[0:1], s[0:1], 1
	v_lshl_add_u64 v[2:3], v[164:165], 0, v[0:1]
	v_dot2c_f32_bf16_e32 v215, v9, v9
	v_dot2c_f32_bf16_e32 v214, v6, v6
	v_lshl_add_u64 v[4:5], v[166:167], 0, v[0:1]
	v_lshl_add_u64 v[8:9], v[162:163], 0, s[0:1]
	global_load_dwordx4 v[92:95], v[2:3], off
	global_load_dwordx4 v[124:127], v[8:9], off
	v_lshl_add_u64 v[2:3], v[172:173], 0, s[0:1]
	v_dot2c_f32_bf16_e32 v214, v7, v7
	v_lshl_add_u64 v[6:7], v[168:169], 0, v[0:1]
	v_lshl_add_u64 v[0:1], v[170:171], 0, v[0:1]
	global_load_dwordx4 v[96:99], v[4:5], off
	global_load_dwordx4 v[120:123], v[2:3], off
	v_lshl_add_u64 v[2:3], v[174:175], 0, s[0:1]
	global_load_dwordx4 v[100:103], v[6:7], off
	global_load_dwordx4 v[116:119], v[2:3], off
	v_lshl_add_u64 v[2:3], v[176:177], 0, s[0:1]
	global_load_dwordx4 v[104:107], v[0:1], off
	global_load_dwordx4 v[112:115], v[2:3], off
	v_ashrrev_i32_e32 v0, 1, v36
	v_dot2c_f32_bf16_e32 v216, v12, v12
	v_dot2c_f32_bf16_e32 v217, v16, v16
	v_and_b32_e32 v218, 0xffffffc0, v0
	v_dot2c_f32_bf16_e32 v216, v13, v13
	v_dot2c_f32_bf16_e32 v217, v17, v17
	v_or_b32_e32 v0, v218, v211
	v_lshl_or_b32 v2, v210, 6, v211
	v_dot2c_f32_bf16_e32 v215, v10, v10
	v_dot2c_f32_bf16_e32 v216, v14, v14
	v_dot2c_f32_bf16_e32 v217, v18, v18
	v_lshl_add_u32 v1, v212, 4, 16
	v_mul_lo_u32 v0, v0, s20
	v_mul_u32_u24_e32 v2, 0x90, v2
	v_dot2c_f32_bf16_e32 v215, v11, v11
	v_dot2c_f32_bf16_e32 v216, v15, v15
	v_dot2c_f32_bf16_e32 v217, v19, v19
	v_add_u32_e32 v219, v1, v0
	v_add_u32_e32 v220, v1, v2
	s_add_i32 s0, s14, 3
	s_add_i32 s1, s14, 4
	s_mov_b32 s14, 0
	v_mov_b32_e32 v0, v157
	v_mov_b32_e32 v1, v157
	v_mov_b32_e32 v2, v157
	v_mov_b32_e32 v3, v157
	v_mov_b32_e32 v4, v157
	v_mov_b32_e32 v5, v157
	v_mov_b32_e32 v6, v157
	v_mov_b32_e32 v7, v157
	v_mov_b32_e32 v8, v157
	v_mov_b32_e32 v9, v157
	v_mov_b32_e32 v10, v157
	v_mov_b32_e32 v11, v157
	v_mov_b32_e32 v12, v157
	v_mov_b32_e32 v13, v157
	v_mov_b32_e32 v14, v157
	v_mov_b32_e32 v15, v157
	v_mov_b32_e32 v16, v157
	v_mov_b32_e32 v17, v157
	v_mov_b32_e32 v18, v157
	v_mov_b32_e32 v19, v157
	v_mov_b32_e32 v20, v157
	v_mov_b32_e32 v21, v157
	v_mov_b32_e32 v22, v157
	v_mov_b32_e32 v23, v157
	v_mov_b32_e32 v24, v157
	v_mov_b32_e32 v25, v157
	v_mov_b32_e32 v26, v157
	v_mov_b32_e32 v27, v157
	v_mov_b32_e32 v28, v157
	v_mov_b32_e32 v29, v157
	v_mov_b32_e32 v30, v157
	v_mov_b32_e32 v31, v157
	v_mov_b32_e32 v32, v157
	v_mov_b32_e32 v33, v157
	v_mov_b32_e32 v34, v157
	v_mov_b32_e32 v35, v157
	v_mov_b32_e32 v36, v157
	v_lshl_or_b32 v250, v209, 11, v156
	v_add_u32_e32 v251, 0x10000, v250
	v_add_u32_e32 v252, 0x20000, v250
	v_add_u32_e32 v253, 0x30000, v250
	s_lshl_b32 s98, s39, 11
	s_add_u32 s98, s52, s98
	s_addc_u32 s99, s53, 0
	s_lshl_b32 s100, s12, 11
	s_add_u32 s100, s80, s100
	s_addc_u32 s101, s81, 0
	ds_read_b128 v[128:131], v219
	ds_read_b128 v[136:139], v220 offset:36864
	ds_read_b128 v[140:143], v220 offset:41472
	ds_read_b128 v[132:135], v219 offset:4608
.LBB0_63:
	s_waitcnt lgkmcnt(3)
	s_waitcnt lgkmcnt(2)
	v_mfma_f32_32x32x16_bf16 v[48:63], v[128:131], v[136:139], v[48:63]
	ds_read_b128 v[144:147], v219 offset:32
	s_waitcnt vmcnt(15)
	v_dot2c_f32_bf16_e32 v214, v80, v80
	ds_write_b128 v213, v[80:83] offset:18432
	s_waitcnt vmcnt(14)
	ds_write_b128 v213, v[72:75] offset:55296
	s_waitcnt lgkmcnt(4)
	v_mfma_f32_32x32x16_bf16 v[32:47], v[128:131], v[140:143], v[32:47]
	ds_read_b128 v[152:155], v220 offset:36896
	s_waitcnt vmcnt(13)
	v_dot2c_f32_bf16_e32 v215, v84, v84
	ds_write_b128 v221, v[84:87] offset:18432
	s_waitcnt vmcnt(12)
	ds_write_b128 v221, v[64:67] offset:55296
	s_waitcnt lgkmcnt(6)
	v_mfma_f32_32x32x16_bf16 v[16:31], v[132:135], v[136:139], v[16:31]
	ds_read_b128 v[228:231], v220 offset:41504
	s_waitcnt vmcnt(11)
	v_dot2c_f32_bf16_e32 v216, v88, v88
	ds_write_b128 v222, v[88:91] offset:18432
	s_waitcnt vmcnt(10)
	ds_write_b128 v222, v[68:71] offset:55296
	v_mfma_f32_32x32x16_bf16 v[0:15], v[132:135], v[140:143], v[0:15]
	ds_read_b128 v[148:151], v219 offset:4640
	s_waitcnt vmcnt(9)
	v_dot2c_f32_bf16_e32 v217, v108, v108
	ds_write_b128 v223, v[108:111] offset:18432
	s_waitcnt vmcnt(8)
	ds_write_b128 v223, v[76:79] offset:55296
	s_waitcnt lgkmcnt(11)
	s_waitcnt lgkmcnt(8)
	v_mfma_f32_32x32x16_bf16 v[48:63], v[144:147], v[152:155], v[48:63]
	ds_read_b128 v[128:131], v219 offset:64
	v_dot2c_f32_bf16_e32 v214, v81, v81
	v_dot2c_f32_bf16_e32 v215, v85, v85
	s_min_u32 s15, s14, 12
	s_add_i32 s15, s0, s15
	s_and_b32 s16, s15, 15
	s_lshl_b32 s16, s16, 7
	s_add_u32 s40, s98, s16
	s_addc_u32 s41, s99, 0
	s_add_u32 s16, s100, s16
	s_addc_u32 s17, s101, 0
	s_waitcnt lgkmcnt(6)
	v_mfma_f32_32x32x16_bf16 v[32:47], v[144:147], v[228:231], v[32:47]
	ds_read_b128 v[136:139], v220 offset:36928
	v_dot2c_f32_bf16_e32 v216, v89, v89
	v_dot2c_f32_bf16_e32 v217, v109, v109
	v_dot2c_f32_bf16_e32 v214, v82, v82
	s_waitcnt lgkmcnt(4)
	v_mfma_f32_32x32x16_bf16 v[16:31], v[148:151], v[152:155], v[16:31]
	ds_read_b128 v[140:143], v220 offset:41536
	v_dot2c_f32_bf16_e32 v215, v86, v86
	v_dot2c_f32_bf16_e32 v216, v90, v90
	v_mfma_f32_32x32x16_bf16 v[0:15], v[148:151], v[228:231], v[0:15]
	ds_read_b128 v[132:135], v219 offset:4672
	v_dot2c_f32_bf16_e32 v217, v110, v110
	v_dot2c_f32_bf16_e32 v214, v83, v83
	s_waitcnt lgkmcnt(3)
	s_waitcnt lgkmcnt(2)
	v_mfma_f32_32x32x16_bf16 v[48:63], v[128:131], v[136:139], v[48:63]
	ds_read_b128 v[144:147], v219 offset:96
	v_dot2c_f32_bf16_e32 v215, v87, v87
	v_dot2c_f32_bf16_e32 v216, v91, v91
	v_dot2c_f32_bf16_e32 v217, v111, v111
	global_load_dwordx4 v[80:83], v250, s[40:41]
	global_load_dwordx4 v[72:75], v250, s[16:17]
	s_waitcnt lgkmcnt(2)
	v_mfma_f32_32x32x16_bf16 v[32:47], v[128:131], v[140:143], v[32:47]
	ds_read_b128 v[152:155], v220 offset:36960
	global_load_dwordx4 v[84:87], v251, s[40:41]
	global_load_dwordx4 v[64:67], v251, s[16:17]
	s_waitcnt lgkmcnt(2)
	v_mfma_f32_32x32x16_bf16 v[16:31], v[132:135], v[136:139], v[16:31]
	ds_read_b128 v[228:231], v220 offset:41568
	global_load_dwordx4 v[88:91], v252, s[40:41]
	global_load_dwordx4 v[68:71], v252, s[16:17]
	v_mfma_f32_32x32x16_bf16 v[0:15], v[132:135], v[140:143], v[0:15]
	ds_read_b128 v[148:151], v219 offset:4704
	global_load_dwordx4 v[108:111], v253, s[40:41]
	global_load_dwordx4 v[76:79], v253, s[16:17]
	s_waitcnt lgkmcnt(0)
	s_barrier
; #define GL_LOAD(KT_, S) { int kt_ = MID ? (((KT_) & 8) | (((KT_) + rot) & 7)) : (((KT_) + rot) & (KT - 1)); kt_ &= ktmask; asm volatile("" : "+s"(kt_)); GL_LD1(0, S) GL_LD1(1, S) GL_LD1(2, S) GL_LD1(3, S) }
; #define GL_STORE(BUF_, S, DOSSQ_) { const bool dossq_ = (DOSSQ_); GL_ST1(0, S, BUF_, ssq0) GL_ST1(1, S, BUF_, ssq1) GL_ST1(2, S, BUF_, ssq2) GL_ST1(3, S, BUF_, ssq3) }
; #define GL_RS(DEN_) { GL_RS1(0, ssq0, DEN_) GL_RS1(1, ssq1, DEN_) GL_RS1(2, ssq2, DEN_) GL_RS1(3, ssq3, DEN_) }
;     ...
;       GL_COMPUTE(1);
;       GL_STORE(0, 0, (kt + 2 < KT) && (!MID || (kt + 2) < 8));
;       GL_LOAD((kt + 4 < KT ? kt + 4 : KT - 1), 0);
;       __syncthreads();
;     }
;   }
;   if (!MID) GL_RS((float)K);
	v_mfma_f32_32x32x16_bf16 v[48:63], v[144:147], v[152:155], v[48:63]
	ds_read_b128 v[128:131], v219 offset:18432
	v_mov_b32_e32 v227, v214
	v_mov_b32_e32 v226, v215
	s_waitcnt vmcnt(15)
	v_dot2c_f32_bf16_e32 v214, v92, v92
	ds_write_b128 v213, v[92:95]
	s_waitcnt vmcnt(14)
	ds_write_b128 v213, v[124:127] offset:36864
	v_mfma_f32_32x32x16_bf16 v[32:47], v[144:147], v[228:231], v[32:47]
	ds_read_b128 v[136:139], v220 offset:55296
	v_mov_b32_e32 v225, v216
	v_mov_b32_e32 v224, v217
	s_waitcnt vmcnt(13)
	v_dot2c_f32_bf16_e32 v215, v96, v96
	ds_write_b128 v221, v[96:99]
	s_waitcnt vmcnt(12)
	ds_write_b128 v221, v[120:123] offset:36864
	v_mfma_f32_32x32x16_bf16 v[16:31], v[148:151], v[152:155], v[16:31]
	ds_read_b128 v[140:143], v220 offset:59904
	s_waitcnt vmcnt(11)
	v_dot2c_f32_bf16_e32 v216, v100, v100
	ds_write_b128 v222, v[100:103]
	s_waitcnt vmcnt(10)
	ds_write_b128 v222, v[116:119] offset:36864
	v_mfma_f32_32x32x16_bf16 v[0:15], v[148:151], v[228:231], v[0:15]
	ds_read_b128 v[132:135], v219 offset:23040
	s_waitcnt vmcnt(9)
	v_dot2c_f32_bf16_e32 v217, v104, v104
	ds_write_b128 v223, v[104:107]
	s_waitcnt vmcnt(8)
	ds_write_b128 v223, v[112:115] offset:36864
	s_waitcnt lgkmcnt(11)
	s_waitcnt lgkmcnt(8)
	v_mfma_f32_32x32x16_bf16 v[48:63], v[128:131], v[136:139], v[48:63]
	ds_read_b128 v[144:147], v219 offset:18464
	v_dot2c_f32_bf16_e32 v214, v93, v93
	v_dot2c_f32_bf16_e32 v215, v97, v97
	s_min_u32 s15, s14, 11
	s_add_i32 s15, s1, s15
	s_and_b32 s16, s15, 15
	s_lshl_b32 s16, s16, 7
	s_add_u32 s40, s98, s16
	s_addc_u32 s41, s99, 0
	s_add_u32 s16, s100, s16
	s_addc_u32 s17, s101, 0
	s_waitcnt lgkmcnt(6)
	v_mfma_f32_32x32x16_bf16 v[32:47], v[128:131], v[140:143], v[32:47]
	ds_read_b128 v[152:155], v220 offset:55328
	v_dot2c_f32_bf16_e32 v216, v101, v101
	v_dot2c_f32_bf16_e32 v217, v105, v105
	v_dot2c_f32_bf16_e32 v214, v94, v94
	s_waitcnt lgkmcnt(4)
	v_mfma_f32_32x32x16_bf16 v[16:31], v[132:135], v[136:139], v[16:31]
	ds_read_b128 v[228:231], v220 offset:59936
	v_dot2c_f32_bf16_e32 v215, v98, v98
	v_dot2c_f32_bf16_e32 v216, v102, v102
	v_mfma_f32_32x32x16_bf16 v[0:15], v[132:135], v[140:143], v[0:15]
	ds_read_b128 v[148:151], v219 offset:23072
	v_dot2c_f32_bf16_e32 v217, v106, v106
	v_dot2c_f32_bf16_e32 v214, v95, v95
	s_waitcnt lgkmcnt(3)
	s_waitcnt lgkmcnt(2)
	v_mfma_f32_32x32x16_bf16 v[48:63], v[144:147], v[152:155], v[48:63]
	ds_read_b128 v[128:131], v219 offset:18496
	v_dot2c_f32_bf16_e32 v215, v99, v99
	v_dot2c_f32_bf16_e32 v216, v103, v103
	v_dot2c_f32_bf16_e32 v217, v107, v107
	global_load_dwordx4 v[92:95], v250, s[40:41]
	global_load_dwordx4 v[124:127], v250, s[16:17]
	s_waitcnt lgkmcnt(2)
	v_mfma_f32_32x32x16_bf16 v[32:47], v[144:147], v[228:231], v[32:47]
	ds_read_b128 v[136:139], v220 offset:55360
	global_load_dwordx4 v[96:99], v251, s[40:41]
	global_load_dwordx4 v[120:123], v251, s[16:17]
	s_waitcnt lgkmcnt(2)
	v_mfma_f32_32x32x16_bf16 v[16:31], v[148:151], v[152:155], v[16:31]
	ds_read_b128 v[140:143], v220 offset:59968
	global_load_dwordx4 v[100:103], v252, s[40:41]
	global_load_dwordx4 v[116:119], v252, s[16:17]
	v_mfma_f32_32x32x16_bf16 v[0:15], v[148:151], v[228:231], v[0:15]
	ds_read_b128 v[132:135], v219 offset:23104
	global_load_dwordx4 v[104:107], v253, s[40:41]
	global_load_dwordx4 v[112:115], v253, s[16:17]
	s_waitcnt lgkmcnt(3)
	s_waitcnt lgkmcnt(2)
	v_mfma_f32_32x32x16_bf16 v[48:63], v[128:131], v[136:139], v[48:63]
	ds_read_b128 v[144:147], v219 offset:18528
	s_add_i32 s15, s14, 2
	s_waitcnt lgkmcnt(2)
	v_mfma_f32_32x32x16_bf16 v[32:47], v[128:131], v[140:143], v[32:47]
	ds_read_b128 v[152:155], v220 offset:55392
	s_waitcnt lgkmcnt(2)
	v_mfma_f32_32x32x16_bf16 v[16:31], v[132:135], v[136:139], v[16:31]
	ds_read_b128 v[228:231], v220 offset:60000
	v_mfma_f32_32x32x16_bf16 v[0:15], v[132:135], v[140:143], v[0:15]
	ds_read_b128 v[148:151], v219 offset:23136
	s_waitcnt lgkmcnt(0)
	s_barrier
	v_mfma_f32_32x32x16_bf16 v[48:63], v[144:147], v[152:155], v[48:63]
	ds_read_b128 v[128:131], v219
	v_mfma_f32_32x32x16_bf16 v[32:47], v[144:147], v[228:231], v[32:47]
	ds_read_b128 v[136:139], v220 offset:36864
	v_mfma_f32_32x32x16_bf16 v[16:31], v[148:151], v[152:155], v[16:31]
	ds_read_b128 v[140:143], v220 offset:41472
	s_cmp_lt_u32 s14, 14
	v_mfma_f32_32x32x16_bf16 v[0:15], v[148:151], v[228:231], v[0:15]
	ds_read_b128 v[132:135], v219 offset:4608
	s_mov_b32 s14, s15
	s_cbranch_scc1 .LBB0_63
	s_waitcnt lgkmcnt(0)
	s_waitcnt vmcnt(9)
	v_and_b32_e32 v65, 64, v206
	v_xor_b32_e32 v64, 1, v206
	v_add_u32_e32 v67, 64, v65
	v_cmp_lt_i32_e32 vcc, v64, v67
	v_xor_b32_e32 v66, 2, v206
	v_xor_b32_e32 v69, 4, v206
	v_cndmask_b32_e32 v64, v206, v64, vcc
	v_lshlrev_b32_e32 v65, 2, v64
	ds_bpermute_b32 v64, v65, v227
	v_cmp_lt_i32_e32 vcc, v66, v67
	s_waitcnt lgkmcnt(0)
	v_add_f32_e32 v64, v227, v64
	v_cndmask_b32_e32 v66, v206, v66, vcc
	v_lshlrev_b32_e32 v66, 2, v66
	ds_bpermute_b32 v68, v66, v64
	v_cmp_lt_i32_e32 vcc, v69, v67
	s_waitcnt lgkmcnt(0)
	v_add_f32_e32 v68, v64, v68
	v_cndmask_b32_e32 v64, v206, v69, vcc
	v_lshlrev_b32_e32 v67, 2, v64
	ds_bpermute_b32 v69, v67, v68
	v_cmp_eq_u32_e32 vcc, 0, v208
	v_lshl_add_u32 v64, v209, 2, 16
	s_and_saveexec_b64 s[14:15], vcc
	s_cbranch_execz .LBB0_66
	s_waitcnt lgkmcnt(0)
	v_add_f32_e32 v68, v68, v69
	v_fmamk_f32 v68, v68, 0x3a800000, v207
	v_mul_f32_e32 v69, 0x4b800000, v68
	v_cmp_gt_f32_e64 s[0:1], s21, v68
	s_nop 1
	v_cndmask_b32_e64 v68, v68, v69, s[0:1]
	v_rsq_f32_e32 v68, v68
	s_nop 0
	v_mul_f32_e32 v69, 0x45800000, v68
	v_cndmask_b32_e64 v68, v68, v69, s[0:1]
	v_add_u32_e32 v69, 0x12000, v64
	ds_write_b32 v69, v68

; DEVI uint32_t pk(float a, float b) { const hwf32x2 v = {a, b}; return __builtin_bit_cast(uint32_t, __builtin_convertvector(v, hwbf16x2)); }
;     ...
; #pragma unroll
;   for (int mi = 0; mi < 2; mi++)
; #pragma unroll
;     for (int ni = 0; ni < 2; ni++)
; #pragma unroll
;       for (int r = 0; r < 16; r++) {
;         const int ri = (r & 3) + 8 * (r >> 2) + 4 * lh;
;         if (TRANS) Ct[(64 * wn + 32 * ni + ri) * CT_LD + 64 * wm + 32 * mi + lr] = acc[mi][ni][r];
;         else Ct[(64 * wm + 32 * mi + ri) * CT_LD + 64 * wn + 32 * ni + lr] = acc[mi][ni][r];
;       }
;   __syncthreads();
; __device__ void phase_gemm_qkv(const P& p, int vb, int nvb, char* smem) {
;     ...
;       int te = threadIdx.x; asm volatile("" : "+v"(te)); const int c8 = te & 15, tq = te >> 4;
;       const int gc = nt * 128 + c8 * 8; const int hd = gc / 96; const int d = gc - hd * 96;
; #pragma unroll
;       for (int i = 0; i < 8; i++) {
;         const int r = tq + 16 * i; const float s = rs[r]; const int prow = mt * 128 + r;
;         if (d < 64) {
;           const float4 v0 = *(const float4*)(Ct + r * CT_LD + c8 * 8), v1 = *(const float4*)(Ct + r * CT_LD + c8 * 8 + 4);
;           *(uint4*)(Q + (size_t)prow * 768 + gc) = make_uint4(pk(v0.x * s, v0.y * s), pk(v0.z * s, v0.w * s), pk(v1.x * s, v1.y * s), pk(v1.z * s, v1.w * s));
;         } else if (d < 80) {
;           const int pos = prow % TP; float o1[8], o2[8];
.LBB0_175:
	s_or_b64 exec, exec, s[0:1]
	v_lshl_or_b32 v64, v169, 2, v173
	s_waitcnt lgkmcnt(0)
	v_lshl_add_u32 v65, v167, 8, 16
	v_lshlrev_b32_e32 v66, 2, v168
	v_mul_lo_u32 v64, v64, s43
	v_add3_u32 v64, v65, v66, v64
	ds_write2_b32 v64, v32, v48 offset1:32
	ds_write2_b32 v64, v33, v49 offset0:132 offset1:164
	v_add_u32_e32 v32, 0x400, v64
	ds_write2_b32 v32, v34, v50 offset0:8 offset1:40
	ds_write2_b32 v32, v35, v51 offset0:140 offset1:172
	v_add_u32_e32 v32, 0x1000, v64
	ds_write2_b32 v32, v36, v52 offset0:32 offset1:64
	ds_write2_b32 v32, v37, v53 offset0:164 offset1:196
	v_add_u32_e32 v32, 0x1400, v64
	ds_write2_b32 v32, v38, v54 offset0:40 offset1:72
	ds_write2_b32 v32, v39, v55 offset0:172 offset1:204
	v_add_u32_e32 v32, 0x2000, v64
	ds_write2_b32 v32, v40, v56 offset0:64 offset1:96
	ds_write2_b32 v32, v41, v57 offset0:196 offset1:228
	v_add_u32_e32 v32, 0x2400, v64
	ds_write2_b32 v32, v42, v58 offset0:72 offset1:104
	ds_write2_b32 v32, v43, v59 offset0:204 offset1:236
	v_add_u32_e32 v32, 0x3000, v64
	ds_write2_b32 v32, v44, v60 offset0:96 offset1:128
	v_add_u32_e32 v32, 0x3200, v64
	ds_write2_b32 v32, v45, v61 offset0:100 offset1:132
	v_add_u32_e32 v32, 0x3400, v64
	ds_write2_b32 v32, v46, v62 offset0:104 offset1:136
	v_add_u32_e32 v32, 0x3600, v64
	ds_write2_b32 v32, v47, v63 offset0:108 offset1:140
	v_add_u32_e32 v32, 0x4000, v64
	ds_write2_b32 v32, v0, v16 offset0:128 offset1:160
	v_add_u32_e32 v0, 0x4400, v64
	ds_write2_b32 v0, v1, v17 offset0:4 offset1:36
	ds_write2_b32 v0, v2, v18 offset0:136 offset1:168
	v_add_u32_e32 v0, 0x4800, v64
	ds_write2_b32 v0, v3, v19 offset0:12 offset1:44
	v_add_u32_e32 v0, 0x5000, v64
	ds_write2_b32 v0, v4, v20 offset0:160 offset1:192
	v_add_u32_e32 v0, 0x5400, v64
	ds_write2_b32 v0, v5, v21 offset0:36 offset1:68
	ds_write2_b32 v0, v6, v22 offset0:168 offset1:200
	v_add_u32_e32 v0, 0x5800, v64
	ds_write2_b32 v0, v7, v23 offset0:44 offset1:76
	v_add_u32_e32 v0, 0x6000, v64
	ds_write2_b32 v0, v8, v24 offset0:192 offset1:224
	v_add_u32_e32 v0, 0x6400, v64
	ds_write2_b32 v0, v9, v25 offset0:68 offset1:100
	ds_write2_b32 v0, v10, v26 offset0:200 offset1:232
	v_add_u32_e32 v0, 0x6800, v64
	ds_write2_b32 v0, v11, v27 offset0:76 offset1:108
	v_add_u32_e32 v0, 0x7200, v64
	ds_write2_b32 v0, v12, v28 offset0:96 offset1:128
	v_add_u32_e32 v0, 0x7400, v64
	ds_write2_b32 v0, v13, v29 offset0:100 offset1:132
	v_add_u32_e32 v0, 0x7600, v64
	ds_write2_b32 v0, v14, v30 offset0:104 offset1:136
	v_add_u32_e32 v0, 0x7800, v64
	ds_write2_b32 v0, v15, v31 offset0:108 offset1:140
	v_mov_b32_e32 v0, v178
	s_waitcnt lgkmcnt(0)
	s_barrier
	s_mov_b32 s0, 0x2aaaaaab
	v_ashrrev_i32_e32 v12, 4, v0
	v_lshlrev_b32_e32 v0, 3, v0
	v_and_b32_e32 v1, 0x78, v0
	v_subrev_u32_e32 v0, s67, v1
	v_add_u32_e32 v0, s62, v0
	v_add_u32_e32 v0, 0x500, v0
	v_mul_hi_i32 v2, v0, s0
	v_lshrrev_b32_e32 v3, 31, v2
	v_lshrrev_b32_e32 v2, 4, v2
	v_add_u32_e32 v2, v2, v3
	s_movk_i32 s0, 0x60
	v_mul_lo_u32 v2, v2, s0
	v_sub_u32_e32 v3, v0, v2
	v_lshl_add_u32 v2, v1, 2, 16
	v_lshl_add_u32 v1, v12, 2, 16
	v_add_u32_e32 v13, 0x12000, v1
	ds_read_b32 v10, v13
	s_movk_i32 s0, 0x50
	v_ashrrev_i32_e32 v1, 31, v0
	v_cmp_lt_i32_e64 s[38:39], 63, v3
	v_cmp_gt_u32_e32 vcc, s0, v3
	v_subrev_u32_e32 v3, 64, v3
	v_lshl_add_u64 v[0:1], v[0:1], 1, s[44:45]
	v_add_u32_e32 v14, s26, v12
	s_and_saveexec_b64 s[0:1], s[38:39]
	s_xor_b64 s[0:1], exec, s[0:1]
	s_cbranch_execz .LBB0_179
	s_and_saveexec_b64 s[66:67], vcc
	s_cbranch_execz .LBB0_178
; DEVI uint32_t pk(float a, float b) { const hwf32x2 v = {a, b}; return __builtin_bit_cast(uint32_t, __builtin_convertvector(v, hwbf16x2)); }
; __device__ void phase_gemm_qkv(const P& p, int vb, int nvb, char* smem) {
;     ...
;       for (int i = 0; i < 8; i++) {
;         const int r = tq + 16 * i; const float s = rs[r]; const int prow = mt * 128 + r;
;         if (d < 64) {
;           const float4 v0 = *(const float4*)(Ct + r * CT_LD + c8 * 8), v1 = *(const float4*)(Ct + r * CT_LD + c8 * 8 + 4);
;           *(uint4*)(Q + (size_t)prow * 768 + gc) = make_uint4(pk(v0.x * s, v0.y * s), pk(v0.z * s, v0.w * s), pk(v1.x * s, v1.y * s), pk(v1.z * s, v1.w * s));
;         } else if (d < 80) {
;           const int pos = prow % TP; float o1[8], o2[8];
; #pragma unroll
;           for (int e = 0; e < 8; e++) {
;             const int c = c8 * 8 + e; const int j = d - 64 + e;
;             const float x1 = Ct[r * CT_LD + c] * s, x2 = Ct[r * CT_LD + c + 16] * s;
;             const float cs = cost[pos * 16 + j], sn = sint[pos * 16 + j];
;             o1[e] = x1 * cs - x2 * sn; o2[e] = x2 * cs + x1 * sn;
;           }
;           *(uint4*)(Q + (size_t)prow * 768 + gc) = make_uint4(pk(o1[0], o1[1]), pk(o1[2], o1[3]), pk(o1[4], o1[5]), pk(o1[6], o1[7]));
;           *(uint4*)(Q + (size_t)prow * 768 + gc + 16) = make_uint4(pk(o2[0], o2[1]), pk(o2[2], o2[3]), pk(o2[4], o2[5]), pk(o2[6], o2[7]));
;         }
	v_add_u32_e32 v240, s26, v12
	v_mul_hi_i32 v241, v240, s35
	v_lshrrev_b32_e32 v242, 31, v241
	v_ashrrev_i32_e32 v241, 10, v241
	v_add_u32_e32 v241, v241, v242
	v_mul_i32_i24_e32 v241, 0x1080, v241
	v_sub_u32_e32 v241, v240, v241
	v_lshl_add_u32 v242, v241, 4, v3
	v_ashrrev_i32_e32 v243, 31, v242
	v_lshlrev_b64 v[242:243], 2, v[242:243]
	v_lshl_add_u64 v[244:245], s[68:69], 0, v[242:243]
	v_lshl_add_u64 v[246:247], s[28:29], 0, v[242:243]
	global_load_dwordx4 v[192:195], v[244:245], off offset:16
	global_load_dwordx4 v[196:199], v[244:245], off
	global_load_dwordx4 v[200:203], v[246:247], off offset:16
	global_load_dwordx4 v[204:207], v[246:247], off
	v_add_u32_e32 v240, 16, v12
	v_add_u32_e32 v240, s26, v240
	v_mul_hi_i32 v241, v240, s35
	v_lshrrev_b32_e32 v242, 31, v241
	v_ashrrev_i32_e32 v241, 10, v241
	v_add_u32_e32 v241, v241, v242
	v_mul_i32_i24_e32 v241, 0x1080, v241
	v_sub_u32_e32 v241, v240, v241
	v_lshl_add_u32 v242, v241, 4, v3
	v_ashrrev_i32_e32 v243, 31, v242
	v_lshlrev_b64 v[242:243], 2, v[242:243]
	v_lshl_add_u64 v[244:245], s[68:69], 0, v[242:243]
	v_lshl_add_u64 v[246:247], s[28:29], 0, v[242:243]
	global_load_dwordx4 v[208:211], v[244:245], off offset:16
	global_load_dwordx4 v[212:215], v[244:245], off
	global_load_dwordx4 v[216:219], v[246:247], off offset:16
	global_load_dwordx4 v[220:223], v[246:247], off
	v_add_u32_e32 v240, 32, v12
	v_add_u32_e32 v240, s26, v240
	v_mul_hi_i32 v241, v240, s35
	v_lshrrev_b32_e32 v242, 31, v241
	v_ashrrev_i32_e32 v241, 10, v241
	v_add_u32_e32 v241, v241, v242
	v_mul_i32_i24_e32 v241, 0x1080, v241
	v_sub_u32_e32 v241, v240, v241
	v_lshl_add_u32 v242, v241, 4, v3
	v_ashrrev_i32_e32 v243, 31, v242
	v_lshlrev_b64 v[242:243], 2, v[242:243]
	v_lshl_add_u64 v[244:245], s[68:69], 0, v[242:243]
	v_lshl_add_u64 v[246:247], s[28:29], 0, v[242:243]
	global_load_dwordx4 v[224:227], v[244:245], off offset:16
	global_load_dwordx4 v[228:231], v[244:245], off
	global_load_dwordx4 v[232:235], v[246:247], off offset:16
	global_load_dwordx4 v[236:239], v[246:247], off
	v_mad_u64_u32 v[8:9], s[40:41], v12, s43, v[2:3]
	ds_read_b128 v[4:7], v8 offset:64
	ds_read_b128 v[24:27], v8
	ds_read_b128 v[28:31], v8 offset:16
	v_mad_i64_i32 v[14:15], s[40:41], v14, s36, v[0:1]
	s_waitcnt lgkmcnt(2)
	v_pk_mul_f32 v[4:5], v[10:11], v[4:5] op_sel_hi:[0,1]
	s_waitcnt lgkmcnt(1)
	v_pk_mul_f32 v[24:25], v[10:11], v[24:25] op_sel_hi:[0,1]
	v_pk_mul_f32 v[6:7], v[10:11], v[6:7] op_sel_hi:[0,1]
	s_waitcnt vmcnt(0)
	v_pk_mul_f32 v[40:41], v[4:5], v[204:205]
	s_nop 0
	v_pk_fma_f32 v[40:41], v[24:25], v[196:197], v[40:41] neg_lo:[0,0,1] neg_hi:[0,0,1]
	v_pk_mul_f32 v[24:25], v[24:25], v[204:205]
	s_nop 0
	v_pk_fma_f32 v[4:5], v[4:5], v[196:197], v[24:25]
	v_pk_mul_f32 v[20:21], v[10:11], v[26:27] op_sel_hi:[0,1]
	v_pk_mul_f32 v[24:25], v[6:7], v[206:207]
	v_cvt_pk_bf16_f32 v4, v4, v5
	v_pk_fma_f32 v[24:25], v[20:21], v[198:199], v[24:25] neg_lo:[0,0,1] neg_hi:[0,0,1]
	v_pk_mul_f32 v[20:21], v[20:21], v[206:207]
	s_nop 0
	v_pk_fma_f32 v[6:7], v[6:7], v[198:199], v[20:21]
	ds_read_b128 v[20:23], v8 offset:80
	v_cvt_pk_bf16_f32 v5, v6, v7
	s_waitcnt lgkmcnt(0)
	v_pk_mul_f32 v[8:9], v[10:11], v[20:21] op_sel_hi:[0,1]
	v_pk_mul_f32 v[20:21], v[10:11], v[28:29] op_sel_hi:[0,1]
	v_pk_mul_f32 v[26:27], v[8:9], v[200:201]
	s_nop 0
	v_pk_fma_f32 v[26:27], v[20:21], v[192:193], v[26:27] neg_lo:[0,0,1] neg_hi:[0,0,1]
	v_pk_mul_f32 v[20:21], v[20:21], v[200:201]
	s_nop 0
	v_pk_fma_f32 v[8:9], v[8:9], v[192:193], v[20:21]
	v_pk_mul_f32 v[16:17], v[10:11], v[22:23] op_sel_hi:[0,1]
	v_pk_mul_f32 v[10:11], v[10:11], v[30:31] op_sel_hi:[0,1]
	v_pk_mul_f32 v[20:21], v[16:17], v[202:203]
	v_cvt_pk_bf16_f32 v6, v8, v9
	v_pk_fma_f32 v[20:21], v[10:11], v[194:195], v[20:21] neg_lo:[0,0,1] neg_hi:[0,0,1]
	v_pk_mul_f32 v[10:11], v[10:11], v[202:203]
	s_nop 0
	v_pk_fma_f32 v[10:11], v[16:17], v[194:195], v[10:11]
	v_cvt_pk_bf16_f32 v16, v40, v41
	v_cvt_pk_bf16_f32 v17, v24, v25
	v_cvt_pk_bf16_f32 v18, v26, v27
	v_cvt_pk_bf16_f32 v19, v20, v21
	v_cvt_pk_bf16_f32 v7, v10, v11
	global_store_dwordx4 v[14:15], v[16:19], off
	global_store_dwordx4 v[14:15], v[4:7], off offset:32

; DEVI uint32_t pk(float a, float b) { const hwf32x2 v = {a, b}; return __builtin_bit_cast(uint32_t, __builtin_convertvector(v, hwbf16x2)); }
; __device__ void phase_gemm_qkv(const P& p, int vb, int nvb, char* smem) {
;     ...
;       for (int i = 0; i < 8; i++) {
;         const int r = tq + 16 * i; const float s = rs[r]; const int prow = mt * 128 + r;
;         if (d < 64) {
;           const float4 v0 = *(const float4*)(Ct + r * CT_LD + c8 * 8), v1 = *(const float4*)(Ct + r * CT_LD + c8 * 8 + 4);
;           *(uint4*)(Q + (size_t)prow * 768 + gc) = make_uint4(pk(v0.x * s, v0.y * s), pk(v0.z * s, v0.w * s), pk(v1.x * s, v1.y * s), pk(v1.z * s, v1.w * s));
;         } else if (d < 80) {
;           const int pos = prow % TP; float o1[8], o2[8];
; #pragma unroll
;           for (int e = 0; e < 8; e++) {
;             const int c = c8 * 8 + e; const int j = d - 64 + e;
;             const float x1 = Ct[r * CT_LD + c] * s, x2 = Ct[r * CT_LD + c + 16] * s;
;             const float cs = cost[pos * 16 + j], sn = sint[pos * 16 + j];
;             o1[e] = x1 * cs - x2 * sn; o2[e] = x2 * cs + x1 * sn;
;           }
;           *(uint4*)(Q + (size_t)prow * 768 + gc) = make_uint4(pk(o1[0], o1[1]), pk(o1[2], o1[3]), pk(o1[4], o1[5]), pk(o1[6], o1[7]));
;           *(uint4*)(Q + (size_t)prow * 768 + gc + 16) = make_uint4(pk(o2[0], o2[1]), pk(o2[2], o2[3]), pk(o2[4], o2[5]), pk(o2[6], o2[7]));
;         }
.LBB0_181:
	s_or_b64 exec, exec, s[0:1]
	s_waitcnt lgkmcnt(0)
	ds_read_b32 v10, v13 offset:64
	v_add_u32_e32 v4, 16, v12
	v_add_u32_e32 v14, s26, v4
	s_and_saveexec_b64 s[0:1], s[38:39]
	s_xor_b64 s[0:1], exec, s[0:1]
	s_cbranch_execz .LBB0_185
	s_and_saveexec_b64 s[66:67], vcc
	s_cbranch_execz .LBB0_184
	v_mad_u64_u32 v[8:9], s[40:41], v4, s43, v[2:3]
	ds_read_b128 v[4:7], v8 offset:64
	ds_read_b128 v[24:27], v8
	ds_read_b128 v[28:31], v8 offset:16
	v_mad_i64_i32 v[14:15], s[40:41], v14, s36, v[0:1]
	s_waitcnt lgkmcnt(2)
	v_pk_mul_f32 v[4:5], v[10:11], v[4:5] op_sel_hi:[0,1]
	s_waitcnt lgkmcnt(1)
	v_pk_mul_f32 v[24:25], v[10:11], v[24:25] op_sel_hi:[0,1]
	v_pk_mul_f32 v[6:7], v[10:11], v[6:7] op_sel_hi:[0,1]
	v_pk_mul_f32 v[40:41], v[4:5], v[220:221]
	s_nop 0
	v_pk_fma_f32 v[40:41], v[24:25], v[212:213], v[40:41] neg_lo:[0,0,1] neg_hi:[0,0,1]
	v_pk_mul_f32 v[24:25], v[24:25], v[220:221]
	s_nop 0
	v_pk_fma_f32 v[4:5], v[4:5], v[212:213], v[24:25]
	v_pk_mul_f32 v[20:21], v[10:11], v[26:27] op_sel_hi:[0,1]
	v_pk_mul_f32 v[24:25], v[6:7], v[222:223]
	v_cvt_pk_bf16_f32 v4, v4, v5
	v_pk_fma_f32 v[24:25], v[20:21], v[214:215], v[24:25] neg_lo:[0,0,1] neg_hi:[0,0,1]
	v_pk_mul_f32 v[20:21], v[20:21], v[222:223]
	s_nop 0
	v_pk_fma_f32 v[6:7], v[6:7], v[214:215], v[20:21]
	ds_read_b128 v[20:23], v8 offset:80
	v_cvt_pk_bf16_f32 v5, v6, v7
	s_waitcnt lgkmcnt(0)
	v_pk_mul_f32 v[8:9], v[10:11], v[20:21] op_sel_hi:[0,1]
	v_pk_mul_f32 v[20:21], v[10:11], v[28:29] op_sel_hi:[0,1]
	v_pk_mul_f32 v[26:27], v[8:9], v[216:217]
	s_nop 0
	v_pk_fma_f32 v[26:27], v[20:21], v[208:209], v[26:27] neg_lo:[0,0,1] neg_hi:[0,0,1]
	v_pk_mul_f32 v[20:21], v[20:21], v[216:217]
	s_nop 0
	v_pk_fma_f32 v[8:9], v[8:9], v[208:209], v[20:21]
	v_pk_mul_f32 v[16:17], v[10:11], v[22:23] op_sel_hi:[0,1]
	v_pk_mul_f32 v[10:11], v[10:11], v[30:31] op_sel_hi:[0,1]
	v_pk_mul_f32 v[20:21], v[16:17], v[218:219]
	v_cvt_pk_bf16_f32 v6, v8, v9
	v_pk_fma_f32 v[20:21], v[10:11], v[210:211], v[20:21] neg_lo:[0,0,1] neg_hi:[0,0,1]
	v_pk_mul_f32 v[10:11], v[10:11], v[218:219]
	s_nop 0
	v_pk_fma_f32 v[10:11], v[16:17], v[210:211], v[10:11]
	v_cvt_pk_bf16_f32 v16, v40, v41
	v_cvt_pk_bf16_f32 v17, v24, v25
	v_cvt_pk_bf16_f32 v18, v26, v27
	v_cvt_pk_bf16_f32 v19, v20, v21
	v_cvt_pk_bf16_f32 v7, v10, v11
	global_store_dwordx4 v[14:15], v[16:19], off
	global_store_dwordx4 v[14:15], v[4:7], off offset:32

; DEVI uint32_t pk(float a, float b) { const hwf32x2 v = {a, b}; return __builtin_bit_cast(uint32_t, __builtin_convertvector(v, hwbf16x2)); }
; __device__ void phase_gemm_qkv(const P& p, int vb, int nvb, char* smem) {
;     ...
;       for (int i = 0; i < 8; i++) {
;         const int r = tq + 16 * i; const float s = rs[r]; const int prow = mt * 128 + r;
;         if (d < 64) {
;           const float4 v0 = *(const float4*)(Ct + r * CT_LD + c8 * 8), v1 = *(const float4*)(Ct + r * CT_LD + c8 * 8 + 4);
;           *(uint4*)(Q + (size_t)prow * 768 + gc) = make_uint4(pk(v0.x * s, v0.y * s), pk(v0.z * s, v0.w * s), pk(v1.x * s, v1.y * s), pk(v1.z * s, v1.w * s));
;         } else if (d < 80) {
;           const int pos = prow % TP; float o1[8], o2[8];
; #pragma unroll
;           for (int e = 0; e < 8; e++) {
;             const int c = c8 * 8 + e; const int j = d - 64 + e;
;             const float x1 = Ct[r * CT_LD + c] * s, x2 = Ct[r * CT_LD + c + 16] * s;
;             const float cs = cost[pos * 16 + j], sn = sint[pos * 16 + j];
;             o1[e] = x1 * cs - x2 * sn; o2[e] = x2 * cs + x1 * sn;
;           }
;           *(uint4*)(Q + (size_t)prow * 768 + gc) = make_uint4(pk(o1[0], o1[1]), pk(o1[2], o1[3]), pk(o1[4], o1[5]), pk(o1[6], o1[7]));
;           *(uint4*)(Q + (size_t)prow * 768 + gc + 16) = make_uint4(pk(o2[0], o2[1]), pk(o2[2], o2[3]), pk(o2[4], o2[5]), pk(o2[6], o2[7]));
;         }
.LBB0_187:
	s_or_b64 exec, exec, s[0:1]
	s_waitcnt lgkmcnt(0)
	ds_read_b32 v10, v13 offset:128
	v_add_u32_e32 v4, 32, v12
	v_add_u32_e32 v14, s26, v4
	s_and_saveexec_b64 s[0:1], s[38:39]
	s_xor_b64 s[0:1], exec, s[0:1]
	s_cbranch_execz .LBB0_191
	s_and_saveexec_b64 s[66:67], vcc
	s_cbranch_execz .LBB0_190
	v_mad_u64_u32 v[8:9], s[40:41], v4, s43, v[2:3]
	ds_read_b128 v[4:7], v8 offset:64
	ds_read_b128 v[24:27], v8
	ds_read_b128 v[28:31], v8 offset:16
	v_mad_i64_i32 v[14:15], s[40:41], v14, s36, v[0:1]
	s_waitcnt lgkmcnt(2)
	v_pk_mul_f32 v[4:5], v[10:11], v[4:5] op_sel_hi:[0,1]
	s_waitcnt lgkmcnt(1)
	v_pk_mul_f32 v[24:25], v[10:11], v[24:25] op_sel_hi:[0,1]
	v_pk_mul_f32 v[6:7], v[10:11], v[6:7] op_sel_hi:[0,1]
	v_pk_mul_f32 v[40:41], v[4:5], v[236:237]
	s_nop 0
	v_pk_fma_f32 v[40:41], v[24:25], v[228:229], v[40:41] neg_lo:[0,0,1] neg_hi:[0,0,1]
	v_pk_mul_f32 v[24:25], v[24:25], v[236:237]
	s_nop 0
	v_pk_fma_f32 v[4:5], v[4:5], v[228:229], v[24:25]
	v_pk_mul_f32 v[20:21], v[10:11], v[26:27] op_sel_hi:[0,1]
	v_pk_mul_f32 v[24:25], v[6:7], v[238:239]
	v_cvt_pk_bf16_f32 v4, v4, v5
	v_pk_fma_f32 v[24:25], v[20:21], v[230:231], v[24:25] neg_lo:[0,0,1] neg_hi:[0,0,1]
	v_pk_mul_f32 v[20:21], v[20:21], v[238:239]
	s_nop 0
	v_pk_fma_f32 v[6:7], v[6:7], v[230:231], v[20:21]
	ds_read_b128 v[20:23], v8 offset:80
	v_cvt_pk_bf16_f32 v5, v6, v7
	s_waitcnt lgkmcnt(0)
	v_pk_mul_f32 v[8:9], v[10:11], v[20:21] op_sel_hi:[0,1]
	v_pk_mul_f32 v[20:21], v[10:11], v[28:29] op_sel_hi:[0,1]
	v_pk_mul_f32 v[26:27], v[8:9], v[232:233]
	s_nop 0
	v_pk_fma_f32 v[26:27], v[20:21], v[224:225], v[26:27] neg_lo:[0,0,1] neg_hi:[0,0,1]
	v_pk_mul_f32 v[20:21], v[20:21], v[232:233]
	s_nop 0
	v_pk_fma_f32 v[8:9], v[8:9], v[224:225], v[20:21]
	v_pk_mul_f32 v[16:17], v[10:11], v[22:23] op_sel_hi:[0,1]
	v_pk_mul_f32 v[10:11], v[10:11], v[30:31] op_sel_hi:[0,1]
	v_pk_mul_f32 v[20:21], v[16:17], v[234:235]
	v_cvt_pk_bf16_f32 v6, v8, v9
	v_pk_fma_f32 v[20:21], v[10:11], v[226:227], v[20:21] neg_lo:[0,0,1] neg_hi:[0,0,1]
	v_pk_mul_f32 v[10:11], v[10:11], v[234:235]
	s_nop 0
	v_pk_fma_f32 v[10:11], v[16:17], v[226:227], v[10:11]
	v_cvt_pk_bf16_f32 v16, v40, v41
	v_cvt_pk_bf16_f32 v17, v24, v25
	v_cvt_pk_bf16_f32 v18, v26, v27
	v_cvt_pk_bf16_f32 v19, v20, v21
	v_cvt_pk_bf16_f32 v7, v10, v11
	global_store_dwordx4 v[14:15], v[16:19], off
	global_store_dwordx4 v[14:15], v[4:7], off offset:32

; DEVI uint32_t pk(float a, float b) { const hwf32x2 v = {a, b}; return __builtin_bit_cast(uint32_t, __builtin_convertvector(v, hwbf16x2)); }
; __device__ void phase_gemm_qkv(const P& p, int vb, int nvb, char* smem) {
;     ...
;       for (int i = 0; i < 8; i++) {
;         const int r = tq + 16 * i; const float s = rs[r]; const int prow = mt * 128 + r;
;         if (d < 64) {
;           const float4 v0 = *(const float4*)(Ct + r * CT_LD + c8 * 8), v1 = *(const float4*)(Ct + r * CT_LD + c8 * 8 + 4);
;           *(uint4*)(Q + (size_t)prow * 768 + gc) = make_uint4(pk(v0.x * s, v0.y * s), pk(v0.z * s, v0.w * s), pk(v1.x * s, v1.y * s), pk(v1.z * s, v1.w * s));
;         } else if (d < 80) {
;           const int pos = prow % TP; float o1[8], o2[8];
; #pragma unroll
;           for (int e = 0; e < 8; e++) {
;             const int c = c8 * 8 + e; const int j = d - 64 + e;
;             const float x1 = Ct[r * CT_LD + c] * s, x2 = Ct[r * CT_LD + c + 16] * s;
;             const float cs = cost[pos * 16 + j], sn = sint[pos * 16 + j];
;             o1[e] = x1 * cs - x2 * sn; o2[e] = x2 * cs + x1 * sn;
;           }
;           *(uint4*)(Q + (size_t)prow * 768 + gc) = make_uint4(pk(o1[0], o1[1]), pk(o1[2], o1[3]), pk(o1[4], o1[5]), pk(o1[6], o1[7]));
;           *(uint4*)(Q + (size_t)prow * 768 + gc + 16) = make_uint4(pk(o2[0], o2[1]), pk(o2[2], o2[3]), pk(o2[4], o2[5]), pk(o2[6], o2[7]));
;         }
.LBB0_193:
	s_or_b64 exec, exec, s[0:1]
	s_waitcnt lgkmcnt(0)
	ds_read_b32 v10, v13 offset:192
	v_add_u32_e32 v4, 48, v12
	v_add_u32_e32 v14, s26, v4
	s_and_saveexec_b64 s[0:1], s[38:39]
	s_xor_b64 s[0:1], exec, s[0:1]
	s_cbranch_execz .LBB0_197
	s_and_saveexec_b64 s[66:67], vcc
	s_cbranch_execz .LBB0_196
	v_add_u32_e32 v240, 48, v12
	v_add_u32_e32 v240, s26, v240
	v_mul_hi_i32 v241, v240, s35
	v_lshrrev_b32_e32 v242, 31, v241
	v_ashrrev_i32_e32 v241, 10, v241
	v_add_u32_e32 v241, v241, v242
	v_mul_i32_i24_e32 v241, 0x1080, v241
	v_sub_u32_e32 v241, v240, v241
	v_lshl_add_u32 v242, v241, 4, v3
	v_ashrrev_i32_e32 v243, 31, v242
	v_lshlrev_b64 v[242:243], 2, v[242:243]
	v_lshl_add_u64 v[244:245], s[68:69], 0, v[242:243]
	v_lshl_add_u64 v[246:247], s[28:29], 0, v[242:243]
	global_load_dwordx4 v[192:195], v[244:245], off offset:16
	global_load_dwordx4 v[196:199], v[244:245], off
	global_load_dwordx4 v[200:203], v[246:247], off offset:16
	global_load_dwordx4 v[204:207], v[246:247], off
	v_add_u32_e32 v240, 64, v12
	v_add_u32_e32 v240, s26, v240
	v_mul_hi_i32 v241, v240, s35
	v_lshrrev_b32_e32 v242, 31, v241
	v_ashrrev_i32_e32 v241, 10, v241
	v_add_u32_e32 v241, v241, v242
	v_mul_i32_i24_e32 v241, 0x1080, v241
	v_sub_u32_e32 v241, v240, v241
	v_lshl_add_u32 v242, v241, 4, v3
	v_ashrrev_i32_e32 v243, 31, v242
	v_lshlrev_b64 v[242:243], 2, v[242:243]
	v_lshl_add_u64 v[244:245], s[68:69], 0, v[242:243]
	v_lshl_add_u64 v[246:247], s[28:29], 0, v[242:243]
	global_load_dwordx4 v[208:211], v[244:245], off offset:16
	global_load_dwordx4 v[212:215], v[244:245], off
	global_load_dwordx4 v[216:219], v[246:247], off offset:16
	global_load_dwordx4 v[220:223], v[246:247], off
	v_add_u32_e32 v240, 80, v12
	v_add_u32_e32 v240, s26, v240
	v_mul_hi_i32 v241, v240, s35
	v_lshrrev_b32_e32 v242, 31, v241
	v_ashrrev_i32_e32 v241, 10, v241
	v_add_u32_e32 v241, v241, v242
	v_mul_i32_i24_e32 v241, 0x1080, v241
	v_sub_u32_e32 v241, v240, v241
	v_lshl_add_u32 v242, v241, 4, v3
	v_ashrrev_i32_e32 v243, 31, v242
	v_lshlrev_b64 v[242:243], 2, v[242:243]
	v_lshl_add_u64 v[244:245], s[68:69], 0, v[242:243]
	v_lshl_add_u64 v[246:247], s[28:29], 0, v[242:243]
	global_load_dwordx4 v[224:227], v[244:245], off offset:16
	global_load_dwordx4 v[228:231], v[244:245], off
	global_load_dwordx4 v[232:235], v[246:247], off offset:16
	global_load_dwordx4 v[236:239], v[246:247], off
	v_mad_u64_u32 v[8:9], s[40:41], v4, s43, v[2:3]
	ds_read_b128 v[4:7], v8 offset:64
	ds_read_b128 v[24:27], v8
	ds_read_b128 v[28:31], v8 offset:16
	v_mad_i64_i32 v[14:15], s[40:41], v14, s36, v[0:1]
	s_waitcnt lgkmcnt(2)
	v_pk_mul_f32 v[4:5], v[10:11], v[4:5] op_sel_hi:[0,1]
	s_waitcnt lgkmcnt(1)
	v_pk_mul_f32 v[24:25], v[10:11], v[24:25] op_sel_hi:[0,1]
	v_pk_mul_f32 v[6:7], v[10:11], v[6:7] op_sel_hi:[0,1]
	s_waitcnt vmcnt(0)
	v_pk_mul_f32 v[40:41], v[4:5], v[204:205]
	s_nop 0
	v_pk_fma_f32 v[40:41], v[24:25], v[196:197], v[40:41] neg_lo:[0,0,1] neg_hi:[0,0,1]
	v_pk_mul_f32 v[24:25], v[24:25], v[204:205]
	s_nop 0
	v_pk_fma_f32 v[4:5], v[4:5], v[196:197], v[24:25]
	v_pk_mul_f32 v[20:21], v[10:11], v[26:27] op_sel_hi:[0,1]
	v_pk_mul_f32 v[24:25], v[6:7], v[206:207]
	v_cvt_pk_bf16_f32 v4, v4, v5
	v_pk_fma_f32 v[24:25], v[20:21], v[198:199], v[24:25] neg_lo:[0,0,1] neg_hi:[0,0,1]
	v_pk_mul_f32 v[20:21], v[20:21], v[206:207]
	s_nop 0
	v_pk_fma_f32 v[6:7], v[6:7], v[198:199], v[20:21]
	ds_read_b128 v[20:23], v8 offset:80
	v_cvt_pk_bf16_f32 v5, v6, v7
	s_waitcnt lgkmcnt(0)
	v_pk_mul_f32 v[8:9], v[10:11], v[20:21] op_sel_hi:[0,1]
	v_pk_mul_f32 v[20:21], v[10:11], v[28:29] op_sel_hi:[0,1]
	v_pk_mul_f32 v[26:27], v[8:9], v[200:201]
	s_nop 0
	v_pk_fma_f32 v[26:27], v[20:21], v[192:193], v[26:27] neg_lo:[0,0,1] neg_hi:[0,0,1]
	v_pk_mul_f32 v[20:21], v[20:21], v[200:201]
	s_nop 0
	v_pk_fma_f32 v[8:9], v[8:9], v[192:193], v[20:21]
	v_pk_mul_f32 v[16:17], v[10:11], v[22:23] op_sel_hi:[0,1]
	v_pk_mul_f32 v[10:11], v[10:11], v[30:31] op_sel_hi:[0,1]
	v_pk_mul_f32 v[20:21], v[16:17], v[202:203]
	v_cvt_pk_bf16_f32 v6, v8, v9
	v_pk_fma_f32 v[20:21], v[10:11], v[194:195], v[20:21] neg_lo:[0,0,1] neg_hi:[0,0,1]
	v_pk_mul_f32 v[10:11], v[10:11], v[202:203]
	s_nop 0
	v_pk_fma_f32 v[10:11], v[16:17], v[194:195], v[10:11]
	v_cvt_pk_bf16_f32 v16, v40, v41
	v_cvt_pk_bf16_f32 v17, v24, v25
	v_cvt_pk_bf16_f32 v18, v26, v27
	v_cvt_pk_bf16_f32 v19, v20, v21
	v_cvt_pk_bf16_f32 v7, v10, v11
	global_store_dwordx4 v[14:15], v[16:19], off
	global_store_dwordx4 v[14:15], v[4:7], off offset:32

; DEVI uint32_t pk(float a, float b) { const hwf32x2 v = {a, b}; return __builtin_bit_cast(uint32_t, __builtin_convertvector(v, hwbf16x2)); }
; __device__ void phase_gemm_qkv(const P& p, int vb, int nvb, char* smem) {
;     ...
;       for (int i = 0; i < 8; i++) {
;         const int r = tq + 16 * i; const float s = rs[r]; const int prow = mt * 128 + r;
;         if (d < 64) {
;           const float4 v0 = *(const float4*)(Ct + r * CT_LD + c8 * 8), v1 = *(const float4*)(Ct + r * CT_LD + c8 * 8 + 4);
;           *(uint4*)(Q + (size_t)prow * 768 + gc) = make_uint4(pk(v0.x * s, v0.y * s), pk(v0.z * s, v0.w * s), pk(v1.x * s, v1.y * s), pk(v1.z * s, v1.w * s));
;         } else if (d < 80) {
;           const int pos = prow % TP; float o1[8], o2[8];
; #pragma unroll
;           for (int e = 0; e < 8; e++) {
;             const int c = c8 * 8 + e; const int j = d - 64 + e;
;             const float x1 = Ct[r * CT_LD + c] * s, x2 = Ct[r * CT_LD + c + 16] * s;
;             const float cs = cost[pos * 16 + j], sn = sint[pos * 16 + j];
;             o1[e] = x1 * cs - x2 * sn; o2[e] = x2 * cs + x1 * sn;
;           }
;           *(uint4*)(Q + (size_t)prow * 768 + gc) = make_uint4(pk(o1[0], o1[1]), pk(o1[2], o1[3]), pk(o1[4], o1[5]), pk(o1[6], o1[7]));
;           *(uint4*)(Q + (size_t)prow * 768 + gc + 16) = make_uint4(pk(o2[0], o2[1]), pk(o2[2], o2[3]), pk(o2[4], o2[5]), pk(o2[6], o2[7]));
;         }
.LBB0_199:
	s_or_b64 exec, exec, s[0:1]
	s_waitcnt lgkmcnt(0)
	ds_read_b32 v10, v13 offset:256
	v_add_u32_e32 v4, 64, v12
	v_add_u32_e32 v14, s26, v4
	s_and_saveexec_b64 s[0:1], s[38:39]
	s_xor_b64 s[0:1], exec, s[0:1]
	s_cbranch_execz .LBB0_203
	s_and_saveexec_b64 s[66:67], vcc
	s_cbranch_execz .LBB0_202
	v_mad_u64_u32 v[8:9], s[40:41], v4, s43, v[2:3]
	ds_read_b128 v[4:7], v8 offset:64
	ds_read_b128 v[24:27], v8
	ds_read_b128 v[28:31], v8 offset:16
	v_mad_i64_i32 v[14:15], s[40:41], v14, s36, v[0:1]
	s_waitcnt lgkmcnt(2)
	v_pk_mul_f32 v[4:5], v[10:11], v[4:5] op_sel_hi:[0,1]
	s_waitcnt lgkmcnt(1)
	v_pk_mul_f32 v[24:25], v[10:11], v[24:25] op_sel_hi:[0,1]
	v_pk_mul_f32 v[6:7], v[10:11], v[6:7] op_sel_hi:[0,1]
	v_pk_mul_f32 v[40:41], v[4:5], v[220:221]
	s_nop 0
	v_pk_fma_f32 v[40:41], v[24:25], v[212:213], v[40:41] neg_lo:[0,0,1] neg_hi:[0,0,1]
	v_pk_mul_f32 v[24:25], v[24:25], v[220:221]
	s_nop 0
	v_pk_fma_f32 v[4:5], v[4:5], v[212:213], v[24:25]
	v_pk_mul_f32 v[20:21], v[10:11], v[26:27] op_sel_hi:[0,1]
	v_pk_mul_f32 v[24:25], v[6:7], v[222:223]
	v_cvt_pk_bf16_f32 v4, v4, v5
	v_pk_fma_f32 v[24:25], v[20:21], v[214:215], v[24:25] neg_lo:[0,0,1] neg_hi:[0,0,1]
	v_pk_mul_f32 v[20:21], v[20:21], v[222:223]
	s_nop 0
	v_pk_fma_f32 v[6:7], v[6:7], v[214:215], v[20:21]
	ds_read_b128 v[20:23], v8 offset:80
	v_cvt_pk_bf16_f32 v5, v6, v7
	s_waitcnt lgkmcnt(0)
	v_pk_mul_f32 v[8:9], v[10:11], v[20:21] op_sel_hi:[0,1]
	v_pk_mul_f32 v[20:21], v[10:11], v[28:29] op_sel_hi:[0,1]
	v_pk_mul_f32 v[26:27], v[8:9], v[216:217]
	s_nop 0
	v_pk_fma_f32 v[26:27], v[20:21], v[208:209], v[26:27] neg_lo:[0,0,1] neg_hi:[0,0,1]
	v_pk_mul_f32 v[20:21], v[20:21], v[216:217]
	s_nop 0
	v_pk_fma_f32 v[8:9], v[8:9], v[208:209], v[20:21]
	v_pk_mul_f32 v[16:17], v[10:11], v[22:23] op_sel_hi:[0,1]
	v_pk_mul_f32 v[10:11], v[10:11], v[30:31] op_sel_hi:[0,1]
	v_pk_mul_f32 v[20:21], v[16:17], v[218:219]
	v_cvt_pk_bf16_f32 v6, v8, v9
	v_pk_fma_f32 v[20:21], v[10:11], v[210:211], v[20:21] neg_lo:[0,0,1] neg_hi:[0,0,1]
	v_pk_mul_f32 v[10:11], v[10:11], v[218:219]
	s_nop 0
	v_pk_fma_f32 v[10:11], v[16:17], v[210:211], v[10:11]
	v_cvt_pk_bf16_f32 v16, v40, v41
	v_cvt_pk_bf16_f32 v17, v24, v25
	v_cvt_pk_bf16_f32 v18, v26, v27
	v_cvt_pk_bf16_f32 v19, v20, v21
	v_cvt_pk_bf16_f32 v7, v10, v11
	global_store_dwordx4 v[14:15], v[16:19], off
	global_store_dwordx4 v[14:15], v[4:7], off offset:32

; DEVI uint32_t pk(float a, float b) { const hwf32x2 v = {a, b}; return __builtin_bit_cast(uint32_t, __builtin_convertvector(v, hwbf16x2)); }
; __device__ void phase_gemm_qkv(const P& p, int vb, int nvb, char* smem) {
;     ...
;       for (int i = 0; i < 8; i++) {
;         const int r = tq + 16 * i; const float s = rs[r]; const int prow = mt * 128 + r;
;         if (d < 64) {
;           const float4 v0 = *(const float4*)(Ct + r * CT_LD + c8 * 8), v1 = *(const float4*)(Ct + r * CT_LD + c8 * 8 + 4);
;           *(uint4*)(Q + (size_t)prow * 768 + gc) = make_uint4(pk(v0.x * s, v0.y * s), pk(v0.z * s, v0.w * s), pk(v1.x * s, v1.y * s), pk(v1.z * s, v1.w * s));
;         } else if (d < 80) {
;           const int pos = prow % TP; float o1[8], o2[8];
; #pragma unroll
;           for (int e = 0; e < 8; e++) {
;             const int c = c8 * 8 + e; const int j = d - 64 + e;
;             const float x1 = Ct[r * CT_LD + c] * s, x2 = Ct[r * CT_LD + c + 16] * s;
;             const float cs = cost[pos * 16 + j], sn = sint[pos * 16 + j];
;             o1[e] = x1 * cs - x2 * sn; o2[e] = x2 * cs + x1 * sn;
;           }
;           *(uint4*)(Q + (size_t)prow * 768 + gc) = make_uint4(pk(o1[0], o1[1]), pk(o1[2], o1[3]), pk(o1[4], o1[5]), pk(o1[6], o1[7]));
;           *(uint4*)(Q + (size_t)prow * 768 + gc + 16) = make_uint4(pk(o2[0], o2[1]), pk(o2[2], o2[3]), pk(o2[4], o2[5]), pk(o2[6], o2[7]));
;         }
.LBB0_205:
	s_or_b64 exec, exec, s[0:1]
	s_waitcnt lgkmcnt(0)
	ds_read_b32 v10, v13 offset:320
	v_add_u32_e32 v4, 0x50, v12
	v_add_u32_e32 v14, s26, v4
	s_and_saveexec_b64 s[0:1], s[38:39]
	s_xor_b64 s[0:1], exec, s[0:1]
	s_cbranch_execz .LBB0_209
	s_and_saveexec_b64 s[66:67], vcc
	s_cbranch_execz .LBB0_208
	v_mad_u64_u32 v[8:9], s[40:41], v4, s43, v[2:3]
	ds_read_b128 v[4:7], v8 offset:64
	ds_read_b128 v[24:27], v8
	ds_read_b128 v[28:31], v8 offset:16
	v_mad_i64_i32 v[14:15], s[40:41], v14, s36, v[0:1]
	s_waitcnt lgkmcnt(2)
	v_pk_mul_f32 v[4:5], v[10:11], v[4:5] op_sel_hi:[0,1]
	s_waitcnt lgkmcnt(1)
	v_pk_mul_f32 v[24:25], v[10:11], v[24:25] op_sel_hi:[0,1]
	v_pk_mul_f32 v[6:7], v[10:11], v[6:7] op_sel_hi:[0,1]
	v_pk_mul_f32 v[40:41], v[4:5], v[236:237]
	s_nop 0
	v_pk_fma_f32 v[40:41], v[24:25], v[228:229], v[40:41] neg_lo:[0,0,1] neg_hi:[0,0,1]
	v_pk_mul_f32 v[24:25], v[24:25], v[236:237]
	s_nop 0
	v_pk_fma_f32 v[4:5], v[4:5], v[228:229], v[24:25]
	v_pk_mul_f32 v[20:21], v[10:11], v[26:27] op_sel_hi:[0,1]
	v_pk_mul_f32 v[24:25], v[6:7], v[238:239]
	v_cvt_pk_bf16_f32 v4, v4, v5
	v_pk_fma_f32 v[24:25], v[20:21], v[230:231], v[24:25] neg_lo:[0,0,1] neg_hi:[0,0,1]
	v_pk_mul_f32 v[20:21], v[20:21], v[238:239]
	s_nop 0
	v_pk_fma_f32 v[6:7], v[6:7], v[230:231], v[20:21]
	ds_read_b128 v[20:23], v8 offset:80
	v_cvt_pk_bf16_f32 v5, v6, v7
	s_waitcnt lgkmcnt(0)
	v_pk_mul_f32 v[8:9], v[10:11], v[20:21] op_sel_hi:[0,1]
	v_pk_mul_f32 v[20:21], v[10:11], v[28:29] op_sel_hi:[0,1]
	v_pk_mul_f32 v[26:27], v[8:9], v[232:233]
	s_nop 0
	v_pk_fma_f32 v[26:27], v[20:21], v[224:225], v[26:27] neg_lo:[0,0,1] neg_hi:[0,0,1]
	v_pk_mul_f32 v[20:21], v[20:21], v[232:233]
	s_nop 0
	v_pk_fma_f32 v[8:9], v[8:9], v[224:225], v[20:21]
	v_pk_mul_f32 v[16:17], v[10:11], v[22:23] op_sel_hi:[0,1]
	v_pk_mul_f32 v[10:11], v[10:11], v[30:31] op_sel_hi:[0,1]
	v_pk_mul_f32 v[20:21], v[16:17], v[234:235]
	v_cvt_pk_bf16_f32 v6, v8, v9
	v_pk_fma_f32 v[20:21], v[10:11], v[226:227], v[20:21] neg_lo:[0,0,1] neg_hi:[0,0,1]
	v_pk_mul_f32 v[10:11], v[10:11], v[234:235]
	s_nop 0
	v_pk_fma_f32 v[10:11], v[16:17], v[226:227], v[10:11]
	v_cvt_pk_bf16_f32 v16, v40, v41
	v_cvt_pk_bf16_f32 v17, v24, v25
	v_cvt_pk_bf16_f32 v18, v26, v27
	v_cvt_pk_bf16_f32 v19, v20, v21
	v_cvt_pk_bf16_f32 v7, v10, v11
	global_store_dwordx4 v[14:15], v[16:19], off
	global_store_dwordx4 v[14:15], v[4:7], off offset:32

; DEVI uint32_t pk(float a, float b) { const hwf32x2 v = {a, b}; return __builtin_bit_cast(uint32_t, __builtin_convertvector(v, hwbf16x2)); }
; __device__ void phase_gemm_qkv(const P& p, int vb, int nvb, char* smem) {
;     ...
;       for (int i = 0; i < 8; i++) {
;         const int r = tq + 16 * i; const float s = rs[r]; const int prow = mt * 128 + r;
;         if (d < 64) {
;           const float4 v0 = *(const float4*)(Ct + r * CT_LD + c8 * 8), v1 = *(const float4*)(Ct + r * CT_LD + c8 * 8 + 4);
;           *(uint4*)(Q + (size_t)prow * 768 + gc) = make_uint4(pk(v0.x * s, v0.y * s), pk(v0.z * s, v0.w * s), pk(v1.x * s, v1.y * s), pk(v1.z * s, v1.w * s));
;         } else if (d < 80) {
;           const int pos = prow % TP; float o1[8], o2[8];
; #pragma unroll
;           for (int e = 0; e < 8; e++) {
;             const int c = c8 * 8 + e; const int j = d - 64 + e;
;             const float x1 = Ct[r * CT_LD + c] * s, x2 = Ct[r * CT_LD + c + 16] * s;
;             const float cs = cost[pos * 16 + j], sn = sint[pos * 16 + j];
;             o1[e] = x1 * cs - x2 * sn; o2[e] = x2 * cs + x1 * sn;
;           }
;           *(uint4*)(Q + (size_t)prow * 768 + gc) = make_uint4(pk(o1[0], o1[1]), pk(o1[2], o1[3]), pk(o1[4], o1[5]), pk(o1[6], o1[7]));
;           *(uint4*)(Q + (size_t)prow * 768 + gc + 16) = make_uint4(pk(o2[0], o2[1]), pk(o2[2], o2[3]), pk(o2[4], o2[5]), pk(o2[6], o2[7]));
;         }
.LBB0_211:
	s_or_b64 exec, exec, s[0:1]
	s_waitcnt lgkmcnt(0)
	ds_read_b32 v10, v13 offset:384
	v_add_u32_e32 v4, 0x60, v12
	v_add_u32_e32 v14, s26, v4
	s_and_saveexec_b64 s[0:1], s[38:39]
	s_xor_b64 s[0:1], exec, s[0:1]
	s_cbranch_execz .LBB0_215
	s_and_saveexec_b64 s[66:67], vcc
	s_cbranch_execz .LBB0_214
	v_add_u32_e32 v240, 96, v12
	v_add_u32_e32 v240, s26, v240
	v_mul_hi_i32 v241, v240, s35
	v_lshrrev_b32_e32 v242, 31, v241
	v_ashrrev_i32_e32 v241, 10, v241
	v_add_u32_e32 v241, v241, v242
	v_mul_i32_i24_e32 v241, 0x1080, v241
	v_sub_u32_e32 v241, v240, v241
	v_lshl_add_u32 v242, v241, 4, v3
	v_ashrrev_i32_e32 v243, 31, v242
	v_lshlrev_b64 v[242:243], 2, v[242:243]
	v_lshl_add_u64 v[244:245], s[68:69], 0, v[242:243]
	v_lshl_add_u64 v[246:247], s[28:29], 0, v[242:243]
	global_load_dwordx4 v[192:195], v[244:245], off offset:16
	global_load_dwordx4 v[196:199], v[244:245], off
	global_load_dwordx4 v[200:203], v[246:247], off offset:16
	global_load_dwordx4 v[204:207], v[246:247], off
	v_mad_u64_u32 v[8:9], s[40:41], v4, s43, v[2:3]
	ds_read_b128 v[4:7], v8 offset:64
	ds_read_b128 v[24:27], v8
	ds_read_b128 v[28:31], v8 offset:16
	v_mad_i64_i32 v[14:15], s[40:41], v14, s36, v[0:1]
	s_waitcnt lgkmcnt(2)
	v_pk_mul_f32 v[4:5], v[10:11], v[4:5] op_sel_hi:[0,1]
	s_waitcnt lgkmcnt(1)
	v_pk_mul_f32 v[24:25], v[10:11], v[24:25] op_sel_hi:[0,1]
	v_pk_mul_f32 v[6:7], v[10:11], v[6:7] op_sel_hi:[0,1]
	s_waitcnt vmcnt(0)
	v_pk_mul_f32 v[40:41], v[4:5], v[204:205]
	s_nop 0
	v_pk_fma_f32 v[40:41], v[24:25], v[196:197], v[40:41] neg_lo:[0,0,1] neg_hi:[0,0,1]
	v_pk_mul_f32 v[24:25], v[24:25], v[204:205]
	s_nop 0
	v_pk_fma_f32 v[4:5], v[4:5], v[196:197], v[24:25]
	v_pk_mul_f32 v[20:21], v[10:11], v[26:27] op_sel_hi:[0,1]
	v_pk_mul_f32 v[24:25], v[6:7], v[206:207]
	v_cvt_pk_bf16_f32 v4, v4, v5
	v_pk_fma_f32 v[24:25], v[20:21], v[198:199], v[24:25] neg_lo:[0,0,1] neg_hi:[0,0,1]
	v_pk_mul_f32 v[20:21], v[20:21], v[206:207]
	s_nop 0
	v_pk_fma_f32 v[6:7], v[6:7], v[198:199], v[20:21]
	ds_read_b128 v[20:23], v8 offset:80
	v_cvt_pk_bf16_f32 v5, v6, v7
	s_waitcnt lgkmcnt(0)
	v_pk_mul_f32 v[8:9], v[10:11], v[20:21] op_sel_hi:[0,1]
	v_pk_mul_f32 v[20:21], v[10:11], v[28:29] op_sel_hi:[0,1]
	v_pk_mul_f32 v[26:27], v[8:9], v[200:201]
	s_nop 0
	v_pk_fma_f32 v[26:27], v[20:21], v[192:193], v[26:27] neg_lo:[0,0,1] neg_hi:[0,0,1]
	v_pk_mul_f32 v[20:21], v[20:21], v[200:201]
	s_nop 0
	v_pk_fma_f32 v[8:9], v[8:9], v[192:193], v[20:21]
	v_pk_mul_f32 v[16:17], v[10:11], v[22:23] op_sel_hi:[0,1]
	v_pk_mul_f32 v[10:11], v[10:11], v[30:31] op_sel_hi:[0,1]
	v_pk_mul_f32 v[20:21], v[16:17], v[202:203]
	v_cvt_pk_bf16_f32 v6, v8, v9
	v_pk_fma_f32 v[20:21], v[10:11], v[194:195], v[20:21] neg_lo:[0,0,1] neg_hi:[0,0,1]
	v_pk_mul_f32 v[10:11], v[10:11], v[202:203]
	s_nop 0
	v_pk_fma_f32 v[10:11], v[16:17], v[194:195], v[10:11]
	v_cvt_pk_bf16_f32 v16, v40, v41
	v_cvt_pk_bf16_f32 v17, v24, v25
	v_cvt_pk_bf16_f32 v18, v26, v27
	v_cvt_pk_bf16_f32 v19, v20, v21
	v_cvt_pk_bf16_f32 v7, v10, v11
	global_store_dwordx4 v[14:15], v[16:19], off
	global_store_dwordx4 v[14:15], v[4:7], off offset:32

; __device__ void phase_gather(const P& p, int vb, int nvb, char* smem) {
;     ...
;     for (int b0 = 0; b0 < 128; b0 += 8) {
;       float dp[8];
; #pragma unroll
;       for (int u = 0; u < 8; u++) {
;         const uint32_t key = mykl[b0 + u];
;         const int e = (int)(key >> 7);
;         const uint4* up = (const uint4*)(U + (size_t)e * 1024 + 16 * j);
;         uint4 uu[4];
; #pragma unroll
;         for (int i = 0; i < 4; i++) uu[i] = up[i * 16];
;         f32x2 d2 = f32x2{0.f, 0.f};
; #pragma unroll
;         for (int i = 0; i < 4; i++) {
;           const uint32_t w[4] = {uu[i].x, uu[i].y, uu[i].z, uu[i].w};
; #pragma unroll
;           for (int q = 0; q < 4; q++) {
;             d2 += __builtin_amdgcn_cvt_pk_f32_fp8((int)w[q], false) * xf[i * 8 + q * 2 + 0];
;             d2 += __builtin_amdgcn_cvt_pk_f32_fp8((int)w[q], true) * xf[i * 8 + q * 2 + 1];
;           }
;         }
;         dp[u] = d2.x + d2.y;
;       }
.Lgu_body:
	s_cmp_eq_u32 s26, 31
	s_cbranch_scc1 .Lgu_last
	s_waitcnt lgkmcnt(0)
	s_waitcnt vmcnt(15)
	v_cvt_pk_f32_fp8_e32 v[104:105], v150
	v_cvt_pk_f32_fp8_sdwa v[106:107], v150 src0_sel:WORD_1
	v_pk_mul_f32 v[112:113], v[104:105], v[214:215]
	v_cvt_pk_f32_fp8_e32 v[108:109], v151
	v_pk_fma_f32 v[112:113], v[106:107], v[216:217], v[112:113]
	v_cvt_pk_f32_fp8_sdwa v[110:111], v151 src0_sel:WORD_1
	v_pk_fma_f32 v[112:113], v[108:109], v[218:219], v[112:113]
	v_cvt_pk_f32_fp8_e32 v[104:105], v152
	v_pk_fma_f32 v[112:113], v[110:111], v[220:221], v[112:113]
	v_cvt_pk_f32_fp8_sdwa v[106:107], v152 src0_sel:WORD_1
	v_pk_fma_f32 v[112:113], v[104:105], v[222:223], v[112:113]
	v_cvt_pk_f32_fp8_e32 v[108:109], v153
	v_pk_fma_f32 v[112:113], v[106:107], v[224:225], v[112:113]
	v_cvt_pk_f32_fp8_sdwa v[110:111], v153 src0_sel:WORD_1
	v_pk_fma_f32 v[112:113], v[108:109], v[226:227], v[112:113]
	v_and_or_b32 v8, v0, s66, v230
	v_pk_fma_f32 v[112:113], v[110:111], v[228:229], v[112:113]
	global_load_dwordx4 v[150:153], v8, s[98:99]
	v_add_f32_e32 v116, v112, v113
	s_waitcnt vmcnt(15)
	v_cvt_pk_f32_fp8_e32 v[104:105], v154
	v_cvt_pk_f32_fp8_sdwa v[106:107], v154 src0_sel:WORD_1
	v_pk_mul_f32 v[112:113], v[104:105], v[214:215]
	v_cvt_pk_f32_fp8_e32 v[108:109], v155
	v_pk_fma_f32 v[112:113], v[106:107], v[216:217], v[112:113]
	v_cvt_pk_f32_fp8_sdwa v[110:111], v155 src0_sel:WORD_1
	v_pk_fma_f32 v[112:113], v[108:109], v[218:219], v[112:113]
	v_cvt_pk_f32_fp8_e32 v[104:105], v156
	v_pk_fma_f32 v[112:113], v[110:111], v[220:221], v[112:113]
	v_cvt_pk_f32_fp8_sdwa v[106:107], v156 src0_sel:WORD_1
	v_pk_fma_f32 v[112:113], v[104:105], v[222:223], v[112:113]
	v_cvt_pk_f32_fp8_e32 v[108:109], v157
	v_pk_fma_f32 v[112:113], v[106:107], v[224:225], v[112:113]
	v_cvt_pk_f32_fp8_sdwa v[110:111], v157 src0_sel:WORD_1
	v_pk_fma_f32 v[112:113], v[108:109], v[226:227], v[112:113]
	v_and_or_b32 v9, v1, s66, v230
	v_pk_fma_f32 v[112:113], v[110:111], v[228:229], v[112:113]
	global_load_dwordx4 v[154:157], v9, s[98:99]
	v_add_f32_e32 v117, v112, v113
	ds_read_b128 v[4:7], v254 offset:16
	s_waitcnt vmcnt(15)
	v_cvt_pk_f32_fp8_e32 v[104:105], v158
	v_cvt_pk_f32_fp8_sdwa v[106:107], v158 src0_sel:WORD_1
	v_pk_mul_f32 v[112:113], v[104:105], v[214:215]
	v_cvt_pk_f32_fp8_e32 v[108:109], v159
	v_pk_fma_f32 v[112:113], v[106:107], v[216:217], v[112:113]
	v_cvt_pk_f32_fp8_sdwa v[110:111], v159 src0_sel:WORD_1
	v_pk_fma_f32 v[112:113], v[108:109], v[218:219], v[112:113]
	v_cvt_pk_f32_fp8_e32 v[104:105], v160
	v_pk_fma_f32 v[112:113], v[110:111], v[220:221], v[112:113]
	v_cvt_pk_f32_fp8_sdwa v[106:107], v160 src0_sel:WORD_1
	v_pk_fma_f32 v[112:113], v[104:105], v[222:223], v[112:113]
	v_cvt_pk_f32_fp8_e32 v[108:109], v161
	v_pk_fma_f32 v[112:113], v[106:107], v[224:225], v[112:113]
	v_cvt_pk_f32_fp8_sdwa v[110:111], v161 src0_sel:WORD_1
	v_pk_fma_f32 v[112:113], v[108:109], v[226:227], v[112:113]
	v_and_or_b32 v8, v2, s66, v230
	v_pk_fma_f32 v[112:113], v[110:111], v[228:229], v[112:113]
	global_load_dwordx4 v[158:161], v8, s[98:99]
	v_add_f32_e32 v118, v112, v113
	s_waitcnt vmcnt(15)
	v_cvt_pk_f32_fp8_e32 v[104:105], v162
	v_cvt_pk_f32_fp8_sdwa v[106:107], v162 src0_sel:WORD_1
	v_pk_mul_f32 v[112:113], v[104:105], v[214:215]
	v_cvt_pk_f32_fp8_e32 v[108:109], v163
	v_pk_fma_f32 v[112:113], v[106:107], v[216:217], v[112:113]
	v_cvt_pk_f32_fp8_sdwa v[110:111], v163 src0_sel:WORD_1
	v_pk_fma_f32 v[112:113], v[108:109], v[218:219], v[112:113]
	v_cvt_pk_f32_fp8_e32 v[104:105], v164
	v_pk_fma_f32 v[112:113], v[110:111], v[220:221], v[112:113]
	v_cvt_pk_f32_fp8_sdwa v[106:107], v164 src0_sel:WORD_1
	v_pk_fma_f32 v[112:113], v[104:105], v[222:223], v[112:113]
	v_cvt_pk_f32_fp8_e32 v[108:109], v165
	v_pk_fma_f32 v[112:113], v[106:107], v[224:225], v[112:113]
	v_cvt_pk_f32_fp8_sdwa v[110:111], v165 src0_sel:WORD_1
	v_pk_fma_f32 v[112:113], v[108:109], v[226:227], v[112:113]
	v_and_or_b32 v9, v3, s66, v230
	v_pk_fma_f32 v[112:113], v[110:111], v[228:229], v[112:113]
	global_load_dwordx4 v[162:165], v9, s[98:99]
	v_add_f32_e32 v119, v112, v113
	s_waitcnt lgkmcnt(0)
	s_waitcnt vmcnt(15)
	v_cvt_pk_f32_fp8_e32 v[104:105], v166
	v_cvt_pk_f32_fp8_sdwa v[106:107], v166 src0_sel:WORD_1
	v_pk_mul_f32 v[112:113], v[104:105], v[214:215]
	v_cvt_pk_f32_fp8_e32 v[108:109], v167
	v_pk_fma_f32 v[112:113], v[106:107], v[216:217], v[112:113]
	v_cvt_pk_f32_fp8_sdwa v[110:111], v167 src0_sel:WORD_1
	v_pk_fma_f32 v[112:113], v[108:109], v[218:219], v[112:113]
	v_cvt_pk_f32_fp8_e32 v[104:105], v168
	v_pk_fma_f32 v[112:113], v[110:111], v[220:221], v[112:113]
	v_cvt_pk_f32_fp8_sdwa v[106:107], v168 src0_sel:WORD_1
	v_pk_fma_f32 v[112:113], v[104:105], v[222:223], v[112:113]
	v_cvt_pk_f32_fp8_e32 v[108:109], v169
	v_pk_fma_f32 v[112:113], v[106:107], v[224:225], v[112:113]
	v_cvt_pk_f32_fp8_sdwa v[110:111], v169 src0_sel:WORD_1
	v_pk_fma_f32 v[112:113], v[108:109], v[226:227], v[112:113]
	v_and_or_b32 v8, v4, s66, v230
	v_pk_fma_f32 v[112:113], v[110:111], v[228:229], v[112:113]
	global_load_dwordx4 v[166:169], v8, s[98:99]
	v_add_f32_e32 v120, v112, v113
	s_waitcnt vmcnt(15)
	v_cvt_pk_f32_fp8_e32 v[104:105], v170
	v_cvt_pk_f32_fp8_sdwa v[106:107], v170 src0_sel:WORD_1
	v_pk_mul_f32 v[112:113], v[104:105], v[214:215]
	v_cvt_pk_f32_fp8_e32 v[108:109], v171
	v_pk_fma_f32 v[112:113], v[106:107], v[216:217], v[112:113]
	v_cvt_pk_f32_fp8_sdwa v[110:111], v171 src0_sel:WORD_1
	v_pk_fma_f32 v[112:113], v[108:109], v[218:219], v[112:113]
	v_cvt_pk_f32_fp8_e32 v[104:105], v172
	v_pk_fma_f32 v[112:113], v[110:111], v[220:221], v[112:113]
	v_cvt_pk_f32_fp8_sdwa v[106:107], v172 src0_sel:WORD_1
	v_pk_fma_f32 v[112:113], v[104:105], v[222:223], v[112:113]
	v_cvt_pk_f32_fp8_e32 v[108:109], v173
	v_pk_fma_f32 v[112:113], v[106:107], v[224:225], v[112:113]
	v_cvt_pk_f32_fp8_sdwa v[110:111], v173 src0_sel:WORD_1
	v_pk_fma_f32 v[112:113], v[108:109], v[226:227], v[112:113]
	v_and_or_b32 v9, v5, s66, v230
	v_pk_fma_f32 v[112:113], v[110:111], v[228:229], v[112:113]
	global_load_dwordx4 v[170:173], v9, s[98:99]
	v_add_f32_e32 v121, v112, v113
	ds_read_b128 v[0:3], v254 offset:32
	s_waitcnt vmcnt(15)
; __device__ void phase_gather(const P& p, int vb, int nvb, char* smem) {
;     ...
;     for (int b0 = 0; b0 < 128; b0 += 8) {
;       float dp[8];
; #pragma unroll
;       for (int u = 0; u < 8; u++) {
;         const uint32_t key = mykl[b0 + u];
;         const int e = (int)(key >> 7);
;         const uint4* up = (const uint4*)(U + (size_t)e * 1024 + 16 * j);
;         uint4 uu[4];
; #pragma unroll
;         for (int i = 0; i < 4; i++) uu[i] = up[i * 16];
;         f32x2 d2 = f32x2{0.f, 0.f};
; #pragma unroll
;         for (int i = 0; i < 4; i++) {
;           const uint32_t w[4] = {uu[i].x, uu[i].y, uu[i].z, uu[i].w};
; #pragma unroll
;           for (int q = 0; q < 4; q++) {
;             d2 += __builtin_amdgcn_cvt_pk_f32_fp8((int)w[q], false) * xf[i * 8 + q * 2 + 0];
;             d2 += __builtin_amdgcn_cvt_pk_f32_fp8((int)w[q], true) * xf[i * 8 + q * 2 + 1];
;           }
;         }
;         dp[u] = d2.x + d2.y;
;       }
;       const bool h8 = (j & 8) != 0, h4 = (j & 4) != 0, h2b = (j & 2) != 0;
;       float q4[4], q2[2];
; #pragma unroll
;       for (int k = 0; k < 4; k++) { const float snd = h8 ? dp[k] : dp[k + 4], kp = h8 ? dp[k + 4] : dp[k]; q4[k] = kp + __shfl_xor(snd, 8); }
; #pragma unroll
;       for (int k = 0; k < 2; k++) { const float snd = h4 ? q4[k] : q4[k + 2], kp = h4 ? q4[k + 2] : q4[k]; q2[k] = kp + __shfl_xor(snd, 4); }
;       const float snd1 = h2b ? q2[0] : q2[1], kp1 = h2b ? q2[1] : q2[0];
;       float q1 = kp1 + __shfl_xor(snd1, 2);
;       q1 += __shfl_xor(q1, 1);
;       if ((j & 1) == 0) mywl[b0 + (j >> 1)] = q1;
	v_cvt_pk_f32_fp8_e32 v[104:105], v174
	v_cvt_pk_f32_fp8_sdwa v[106:107], v174 src0_sel:WORD_1
	v_pk_mul_f32 v[112:113], v[104:105], v[214:215]
	v_cvt_pk_f32_fp8_e32 v[108:109], v175
	v_pk_fma_f32 v[112:113], v[106:107], v[216:217], v[112:113]
	v_cvt_pk_f32_fp8_sdwa v[110:111], v175 src0_sel:WORD_1
	v_pk_fma_f32 v[112:113], v[108:109], v[218:219], v[112:113]
	v_cvt_pk_f32_fp8_e32 v[104:105], v176
	v_pk_fma_f32 v[112:113], v[110:111], v[220:221], v[112:113]
	v_cvt_pk_f32_fp8_sdwa v[106:107], v176 src0_sel:WORD_1
	v_pk_fma_f32 v[112:113], v[104:105], v[222:223], v[112:113]
	v_cvt_pk_f32_fp8_e32 v[108:109], v177
	v_pk_fma_f32 v[112:113], v[106:107], v[224:225], v[112:113]
	v_cvt_pk_f32_fp8_sdwa v[110:111], v177 src0_sel:WORD_1
	v_pk_fma_f32 v[112:113], v[108:109], v[226:227], v[112:113]
	v_and_or_b32 v8, v6, s66, v230
	v_pk_fma_f32 v[112:113], v[110:111], v[228:229], v[112:113]
	global_load_dwordx4 v[174:177], v8, s[98:99]
	v_add_f32_e32 v122, v112, v113
	s_waitcnt vmcnt(15)
	v_cvt_pk_f32_fp8_e32 v[104:105], v178
	v_cvt_pk_f32_fp8_sdwa v[106:107], v178 src0_sel:WORD_1
	v_pk_mul_f32 v[112:113], v[104:105], v[214:215]
	v_cvt_pk_f32_fp8_e32 v[108:109], v179
	v_pk_fma_f32 v[112:113], v[106:107], v[216:217], v[112:113]
	v_cvt_pk_f32_fp8_sdwa v[110:111], v179 src0_sel:WORD_1
	v_pk_fma_f32 v[112:113], v[108:109], v[218:219], v[112:113]
	v_cvt_pk_f32_fp8_e32 v[104:105], v180
	v_pk_fma_f32 v[112:113], v[110:111], v[220:221], v[112:113]
	v_cvt_pk_f32_fp8_sdwa v[106:107], v180 src0_sel:WORD_1
	v_pk_fma_f32 v[112:113], v[104:105], v[222:223], v[112:113]
	v_cvt_pk_f32_fp8_e32 v[108:109], v181
	v_pk_fma_f32 v[112:113], v[106:107], v[224:225], v[112:113]
	v_cvt_pk_f32_fp8_sdwa v[110:111], v181 src0_sel:WORD_1
	v_pk_fma_f32 v[112:113], v[108:109], v[226:227], v[112:113]
	v_and_or_b32 v9, v7, s66, v230
	v_pk_fma_f32 v[112:113], v[110:111], v[228:229], v[112:113]
	global_load_dwordx4 v[178:181], v9, s[98:99]
	v_add_f32_e32 v123, v112, v113
	v_add_f32_dpp v10, v116, v116 row_ror:8 row_mask:0xf bank_mask:0x3
	v_add_f32_dpp v11, v117, v117 row_ror:8 row_mask:0xf bank_mask:0x3
	v_add_f32_dpp v12, v118, v118 row_ror:8 row_mask:0xf bank_mask:0x3
	v_add_f32_dpp v124, v119, v119 row_ror:8 row_mask:0xf bank_mask:0x3
	v_add_f32_dpp v10, v120, v120 row_ror:8 row_mask:0xf bank_mask:0xc
	v_add_f32_dpp v11, v121, v121 row_ror:8 row_mask:0xf bank_mask:0xc
	v_add_f32_dpp v12, v122, v122 row_ror:8 row_mask:0xf bank_mask:0xc
	v_add_f32_dpp v124, v123, v123 row_ror:8 row_mask:0xf bank_mask:0xc
	s_nop 0
	v_add_f32_dpp v125, v10, v10 row_shl:4 row_mask:0xf bank_mask:0x5
	v_add_f32_dpp v246, v11, v11 row_shl:4 row_mask:0xf bank_mask:0x5
	v_add_f32_dpp v125, v12, v12 row_shr:4 row_mask:0xf bank_mask:0xa
	v_add_f32_dpp v246, v124, v124 row_shr:4 row_mask:0xf bank_mask:0xa
	s_nop 1
	v_add_f32_dpp v247, v125, v125 quad_perm:[2,3,0,1] row_mask:0xf bank_mask:0xf
	v_add_f32_dpp v249, v246, v246 quad_perm:[2,3,0,1] row_mask:0xf bank_mask:0xf
	s_nop 0
	v_cndmask_b32_e64 v252, v249, v247, s[2:3]
	s_nop 1
	v_add_f32_dpp v253, v252, v252 quad_perm:[1,0,3,2] row_mask:0xf bank_mask:0xf
	s_and_saveexec_b64 s[20:21], s[4:5]
	ds_add_f32 v251, v253 offset:2048
	s_mov_b64 exec, s[20:21]
	s_waitcnt lgkmcnt(0)
	s_waitcnt vmcnt(15)
	v_cvt_pk_f32_fp8_e32 v[104:105], v182
	v_cvt_pk_f32_fp8_sdwa v[106:107], v182 src0_sel:WORD_1
	v_pk_mul_f32 v[112:113], v[104:105], v[214:215]
	v_cvt_pk_f32_fp8_e32 v[108:109], v183
	v_pk_fma_f32 v[112:113], v[106:107], v[216:217], v[112:113]
	v_cvt_pk_f32_fp8_sdwa v[110:111], v183 src0_sel:WORD_1
	v_pk_fma_f32 v[112:113], v[108:109], v[218:219], v[112:113]
	v_cvt_pk_f32_fp8_e32 v[104:105], v184
	v_pk_fma_f32 v[112:113], v[110:111], v[220:221], v[112:113]
	v_cvt_pk_f32_fp8_sdwa v[106:107], v184 src0_sel:WORD_1
	v_pk_fma_f32 v[112:113], v[104:105], v[222:223], v[112:113]
	v_cvt_pk_f32_fp8_e32 v[108:109], v185
	v_pk_fma_f32 v[112:113], v[106:107], v[224:225], v[112:113]
	v_cvt_pk_f32_fp8_sdwa v[110:111], v185 src0_sel:WORD_1
	v_pk_fma_f32 v[112:113], v[108:109], v[226:227], v[112:113]
	v_and_or_b32 v8, v0, s66, v230
	v_pk_fma_f32 v[112:113], v[110:111], v[228:229], v[112:113]
	global_load_dwordx4 v[182:185], v8, s[98:99]
	v_add_f32_e32 v116, v112, v113
	s_waitcnt vmcnt(15)
	v_cvt_pk_f32_fp8_e32 v[104:105], v186
	v_cvt_pk_f32_fp8_sdwa v[106:107], v186 src0_sel:WORD_1
	v_pk_mul_f32 v[112:113], v[104:105], v[214:215]
	v_cvt_pk_f32_fp8_e32 v[108:109], v187
	v_pk_fma_f32 v[112:113], v[106:107], v[216:217], v[112:113]
	v_cvt_pk_f32_fp8_sdwa v[110:111], v187 src0_sel:WORD_1
	v_pk_fma_f32 v[112:113], v[108:109], v[218:219], v[112:113]
	v_cvt_pk_f32_fp8_e32 v[104:105], v188
	v_pk_fma_f32 v[112:113], v[110:111], v[220:221], v[112:113]
	v_cvt_pk_f32_fp8_sdwa v[106:107], v188 src0_sel:WORD_1
	v_pk_fma_f32 v[112:113], v[104:105], v[222:223], v[112:113]
	v_cvt_pk_f32_fp8_e32 v[108:109], v189
	v_pk_fma_f32 v[112:113], v[106:107], v[224:225], v[112:113]
	v_cvt_pk_f32_fp8_sdwa v[110:111], v189 src0_sel:WORD_1
	v_pk_fma_f32 v[112:113], v[108:109], v[226:227], v[112:113]
	v_and_or_b32 v9, v1, s66, v230
	v_pk_fma_f32 v[112:113], v[110:111], v[228:229], v[112:113]
	global_load_dwordx4 v[186:189], v9, s[98:99]
	v_add_f32_e32 v117, v112, v113
	ds_read_b128 v[4:7], v254 offset:48
	s_waitcnt vmcnt(15)
; __device__ void phase_gather(const P& p, int vb, int nvb, char* smem) {
;     ...
;       for (int u = 0; u < 8; u++) {
;         const uint32_t key = mykl[b0 + u];
;         const int e = (int)(key >> 7);
;         const uint4* up = (const uint4*)(U + (size_t)e * 1024 + 16 * j);
;         uint4 uu[4];
; #pragma unroll
;         for (int i = 0; i < 4; i++) uu[i] = up[i * 16];
;         f32x2 d2 = f32x2{0.f, 0.f};
; #pragma unroll
;         for (int i = 0; i < 4; i++) {
;           const uint32_t w[4] = {uu[i].x, uu[i].y, uu[i].z, uu[i].w};
; #pragma unroll
;           for (int q = 0; q < 4; q++) {
;             d2 += __builtin_amdgcn_cvt_pk_f32_fp8((int)w[q], false) * xf[i * 8 + q * 2 + 0];
;             d2 += __builtin_amdgcn_cvt_pk_f32_fp8((int)w[q], true) * xf[i * 8 + q * 2 + 1];
;           }
;         }
;         dp[u] = d2.x + d2.y;
	v_cvt_pk_f32_fp8_e32 v[104:105], v190
	v_cvt_pk_f32_fp8_sdwa v[106:107], v190 src0_sel:WORD_1
	v_pk_mul_f32 v[112:113], v[104:105], v[214:215]
	v_cvt_pk_f32_fp8_e32 v[108:109], v191
	v_pk_fma_f32 v[112:113], v[106:107], v[216:217], v[112:113]
	v_cvt_pk_f32_fp8_sdwa v[110:111], v191 src0_sel:WORD_1
	v_pk_fma_f32 v[112:113], v[108:109], v[218:219], v[112:113]
	v_cvt_pk_f32_fp8_e32 v[104:105], v192
	v_pk_fma_f32 v[112:113], v[110:111], v[220:221], v[112:113]
	v_cvt_pk_f32_fp8_sdwa v[106:107], v192 src0_sel:WORD_1
	v_pk_fma_f32 v[112:113], v[104:105], v[222:223], v[112:113]
	v_cvt_pk_f32_fp8_e32 v[108:109], v193
	v_pk_fma_f32 v[112:113], v[106:107], v[224:225], v[112:113]
	v_cvt_pk_f32_fp8_sdwa v[110:111], v193 src0_sel:WORD_1
	v_pk_fma_f32 v[112:113], v[108:109], v[226:227], v[112:113]
	v_and_or_b32 v8, v2, s66, v230
	v_pk_fma_f32 v[112:113], v[110:111], v[228:229], v[112:113]
	global_load_dwordx4 v[190:193], v8, s[98:99]
	v_add_f32_e32 v118, v112, v113
	s_waitcnt vmcnt(15)
	v_cvt_pk_f32_fp8_e32 v[104:105], v194
	v_cvt_pk_f32_fp8_sdwa v[106:107], v194 src0_sel:WORD_1
	v_pk_mul_f32 v[112:113], v[104:105], v[214:215]
	v_cvt_pk_f32_fp8_e32 v[108:109], v195
	v_pk_fma_f32 v[112:113], v[106:107], v[216:217], v[112:113]
	v_cvt_pk_f32_fp8_sdwa v[110:111], v195 src0_sel:WORD_1
	v_pk_fma_f32 v[112:113], v[108:109], v[218:219], v[112:113]
	v_cvt_pk_f32_fp8_e32 v[104:105], v196
	v_pk_fma_f32 v[112:113], v[110:111], v[220:221], v[112:113]
	v_cvt_pk_f32_fp8_sdwa v[106:107], v196 src0_sel:WORD_1
	v_pk_fma_f32 v[112:113], v[104:105], v[222:223], v[112:113]
	v_cvt_pk_f32_fp8_e32 v[108:109], v197
	v_pk_fma_f32 v[112:113], v[106:107], v[224:225], v[112:113]
	v_cvt_pk_f32_fp8_sdwa v[110:111], v197 src0_sel:WORD_1
	v_pk_fma_f32 v[112:113], v[108:109], v[226:227], v[112:113]
	v_and_or_b32 v9, v3, s66, v230
	v_pk_fma_f32 v[112:113], v[110:111], v[228:229], v[112:113]
	global_load_dwordx4 v[194:197], v9, s[98:99]
	v_add_f32_e32 v119, v112, v113
	s_waitcnt lgkmcnt(0)
	s_waitcnt vmcnt(15)
	v_cvt_pk_f32_fp8_e32 v[104:105], v198
	v_cvt_pk_f32_fp8_sdwa v[106:107], v198 src0_sel:WORD_1
	v_pk_mul_f32 v[112:113], v[104:105], v[214:215]
	v_cvt_pk_f32_fp8_e32 v[108:109], v199
	v_pk_fma_f32 v[112:113], v[106:107], v[216:217], v[112:113]
	v_cvt_pk_f32_fp8_sdwa v[110:111], v199 src0_sel:WORD_1
	v_pk_fma_f32 v[112:113], v[108:109], v[218:219], v[112:113]
	v_cvt_pk_f32_fp8_e32 v[104:105], v200
	v_pk_fma_f32 v[112:113], v[110:111], v[220:221], v[112:113]
	v_cvt_pk_f32_fp8_sdwa v[106:107], v200 src0_sel:WORD_1
	v_pk_fma_f32 v[112:113], v[104:105], v[222:223], v[112:113]
	v_cvt_pk_f32_fp8_e32 v[108:109], v201
	v_pk_fma_f32 v[112:113], v[106:107], v[224:225], v[112:113]
	v_cvt_pk_f32_fp8_sdwa v[110:111], v201 src0_sel:WORD_1
	v_pk_fma_f32 v[112:113], v[108:109], v[226:227], v[112:113]
	v_and_or_b32 v8, v4, s66, v230
	v_pk_fma_f32 v[112:113], v[110:111], v[228:229], v[112:113]
	global_load_dwordx4 v[198:201], v8, s[98:99]
	v_add_f32_e32 v120, v112, v113
	s_add_i32 s27, s26, 2
	s_and_b32 s27, s27, 7
	s_lshl_b32 s27, s27, 6
	v_add_u32_e32 v254, s27, v133
	s_waitcnt vmcnt(15)
	v_cvt_pk_f32_fp8_e32 v[104:105], v202
	v_cvt_pk_f32_fp8_sdwa v[106:107], v202 src0_sel:WORD_1
	v_pk_mul_f32 v[112:113], v[104:105], v[214:215]
	v_cvt_pk_f32_fp8_e32 v[108:109], v203
	v_pk_fma_f32 v[112:113], v[106:107], v[216:217], v[112:113]
	v_cvt_pk_f32_fp8_sdwa v[110:111], v203 src0_sel:WORD_1
	v_pk_fma_f32 v[112:113], v[108:109], v[218:219], v[112:113]
	v_cvt_pk_f32_fp8_e32 v[104:105], v204
	v_pk_fma_f32 v[112:113], v[110:111], v[220:221], v[112:113]
	v_cvt_pk_f32_fp8_sdwa v[106:107], v204 src0_sel:WORD_1
	v_pk_fma_f32 v[112:113], v[104:105], v[222:223], v[112:113]
	v_cvt_pk_f32_fp8_e32 v[108:109], v205
	v_pk_fma_f32 v[112:113], v[106:107], v[224:225], v[112:113]
	v_cvt_pk_f32_fp8_sdwa v[110:111], v205 src0_sel:WORD_1
	v_pk_fma_f32 v[112:113], v[108:109], v[226:227], v[112:113]
	v_and_or_b32 v9, v5, s66, v230
	v_pk_fma_f32 v[112:113], v[110:111], v[228:229], v[112:113]
	global_load_dwordx4 v[202:205], v9, s[98:99]
	v_add_f32_e32 v121, v112, v113
	ds_read_b128 v[0:3], v254
	s_waitcnt vmcnt(15)
; __device__ void phase_gather(const P& p, int vb, int nvb, char* smem) {
;     ...
;       for (int u = 0; u < 8; u++) {
;         const uint32_t key = mykl[b0 + u];
;         const int e = (int)(key >> 7);
;         const uint4* up = (const uint4*)(U + (size_t)e * 1024 + 16 * j);
;         uint4 uu[4];
; #pragma unroll
;         for (int i = 0; i < 4; i++) uu[i] = up[i * 16];
;         f32x2 d2 = f32x2{0.f, 0.f};
; #pragma unroll
;         for (int i = 0; i < 4; i++) {
;           const uint32_t w[4] = {uu[i].x, uu[i].y, uu[i].z, uu[i].w};
; #pragma unroll
;           for (int q = 0; q < 4; q++) {
;             d2 += __builtin_amdgcn_cvt_pk_f32_fp8((int)w[q], false) * xf[i * 8 + q * 2 + 0];
;             d2 += __builtin_amdgcn_cvt_pk_f32_fp8((int)w[q], true) * xf[i * 8 + q * 2 + 1];
;           }
;         }
;         dp[u] = d2.x + d2.y;
;       }
;       const bool h8 = (j & 8) != 0, h4 = (j & 4) != 0, h2b = (j & 2) != 0;
;       float q4[4], q2[2];
; #pragma unroll
;       for (int k = 0; k < 4; k++) { const float snd = h8 ? dp[k] : dp[k + 4], kp = h8 ? dp[k + 4] : dp[k]; q4[k] = kp + __shfl_xor(snd, 8); }
; #pragma unroll
;       for (int k = 0; k < 2; k++) { const float snd = h4 ? q4[k] : q4[k + 2], kp = h4 ? q4[k + 2] : q4[k]; q2[k] = kp + __shfl_xor(snd, 4); }
;       const float snd1 = h2b ? q2[0] : q2[1], kp1 = h2b ? q2[1] : q2[0];
;       float q1 = kp1 + __shfl_xor(snd1, 2);
;       q1 += __shfl_xor(q1, 1);
;       if ((j & 1) == 0) mywl[b0 + (j >> 1)] = q1;
	v_cvt_pk_f32_fp8_e32 v[104:105], v206
	v_cvt_pk_f32_fp8_sdwa v[106:107], v206 src0_sel:WORD_1
	v_pk_mul_f32 v[112:113], v[104:105], v[214:215]
	v_cvt_pk_f32_fp8_e32 v[108:109], v207
	v_pk_fma_f32 v[112:113], v[106:107], v[216:217], v[112:113]
	v_cvt_pk_f32_fp8_sdwa v[110:111], v207 src0_sel:WORD_1
	v_pk_fma_f32 v[112:113], v[108:109], v[218:219], v[112:113]
	v_cvt_pk_f32_fp8_e32 v[104:105], v208
	v_pk_fma_f32 v[112:113], v[110:111], v[220:221], v[112:113]
	v_cvt_pk_f32_fp8_sdwa v[106:107], v208 src0_sel:WORD_1
	v_pk_fma_f32 v[112:113], v[104:105], v[222:223], v[112:113]
	v_cvt_pk_f32_fp8_e32 v[108:109], v209
	v_pk_fma_f32 v[112:113], v[106:107], v[224:225], v[112:113]
	v_cvt_pk_f32_fp8_sdwa v[110:111], v209 src0_sel:WORD_1
	v_pk_fma_f32 v[112:113], v[108:109], v[226:227], v[112:113]
	v_and_or_b32 v8, v6, s66, v230
	v_pk_fma_f32 v[112:113], v[110:111], v[228:229], v[112:113]
	global_load_dwordx4 v[206:209], v8, s[98:99]
	v_add_f32_e32 v122, v112, v113
	s_waitcnt vmcnt(15)
	v_cvt_pk_f32_fp8_e32 v[104:105], v210
	v_cvt_pk_f32_fp8_sdwa v[106:107], v210 src0_sel:WORD_1
	v_pk_mul_f32 v[112:113], v[104:105], v[214:215]
	v_cvt_pk_f32_fp8_e32 v[108:109], v211
	v_pk_fma_f32 v[112:113], v[106:107], v[216:217], v[112:113]
	v_cvt_pk_f32_fp8_sdwa v[110:111], v211 src0_sel:WORD_1
	v_pk_fma_f32 v[112:113], v[108:109], v[218:219], v[112:113]
	v_cvt_pk_f32_fp8_e32 v[104:105], v212
	v_pk_fma_f32 v[112:113], v[110:111], v[220:221], v[112:113]
	v_cvt_pk_f32_fp8_sdwa v[106:107], v212 src0_sel:WORD_1
	v_pk_fma_f32 v[112:113], v[104:105], v[222:223], v[112:113]
	v_cvt_pk_f32_fp8_e32 v[108:109], v213
	v_pk_fma_f32 v[112:113], v[106:107], v[224:225], v[112:113]
	v_cvt_pk_f32_fp8_sdwa v[110:111], v213 src0_sel:WORD_1
	v_pk_fma_f32 v[112:113], v[108:109], v[226:227], v[112:113]
	v_and_or_b32 v9, v7, s66, v230
	v_pk_fma_f32 v[112:113], v[110:111], v[228:229], v[112:113]
	global_load_dwordx4 v[210:213], v9, s[98:99]
	v_add_f32_e32 v123, v112, v113
	v_add_f32_dpp v10, v116, v116 row_ror:8 row_mask:0xf bank_mask:0x3
	v_add_f32_dpp v11, v117, v117 row_ror:8 row_mask:0xf bank_mask:0x3
	v_add_f32_dpp v12, v118, v118 row_ror:8 row_mask:0xf bank_mask:0x3
	v_add_f32_dpp v124, v119, v119 row_ror:8 row_mask:0xf bank_mask:0x3
	v_add_f32_dpp v10, v120, v120 row_ror:8 row_mask:0xf bank_mask:0xc
	v_add_f32_dpp v11, v121, v121 row_ror:8 row_mask:0xf bank_mask:0xc
	v_add_f32_dpp v12, v122, v122 row_ror:8 row_mask:0xf bank_mask:0xc
	v_add_f32_dpp v124, v123, v123 row_ror:8 row_mask:0xf bank_mask:0xc
	s_nop 0
	v_add_f32_dpp v125, v10, v10 row_shl:4 row_mask:0xf bank_mask:0x5
	v_add_f32_dpp v246, v11, v11 row_shl:4 row_mask:0xf bank_mask:0x5
	v_add_f32_dpp v125, v12, v12 row_shr:4 row_mask:0xf bank_mask:0xa
	v_add_f32_dpp v246, v124, v124 row_shr:4 row_mask:0xf bank_mask:0xa
	s_nop 1
	v_add_f32_dpp v247, v125, v125 quad_perm:[2,3,0,1] row_mask:0xf bank_mask:0xf
	v_add_f32_dpp v249, v246, v246 quad_perm:[2,3,0,1] row_mask:0xf bank_mask:0xf
	s_nop 0
	v_cndmask_b32_e64 v252, v249, v247, s[2:3]
	s_nop 1
	v_add_f32_dpp v253, v252, v252 quad_perm:[1,0,3,2] row_mask:0xf bank_mask:0xf
	s_and_saveexec_b64 s[20:21], s[4:5]
	ds_add_f32 v251, v253 offset:2080
	s_mov_b64 exec, s[20:21]
	s_add_i32 s26, s26, 1
	s_add_i32 s20, s26, 1
	s_lshr_b32 s27, s20, 3
	s_and_b32 s27, s27, 3
	s_lshl_b32 s27, s27, 22
	v_add_u32_e32 v230, s27, v250
	s_and_b32 s27, s26, 7
	s_lshl_b32 s27, s27, 6
	v_add_u32_e32 v251, s27, v231
	s_and_b32 s20, s26, 7
	s_cmp_lg_u32 s20, 0
	s_cbranch_scc1 .Lgu_body
	s_lshr_b32 s27, s26, 3
	s_and_b32 s27, s27, 3
	s_cmp_eq_u32 s27, 0
	s_cbranch_scc1 .Lgu_s_0
	s_cmp_eq_u32 s27, 1
	s_cbranch_scc1 .Lgu_s_1
	s_cmp_eq_u32 s27, 2
	s_cbranch_scc1 .Lgu_s_2
	v_mov_b32_e32 v214, v80
	v_mov_b32_e32 v215, v81
	v_mov_b32_e32 v216, v82
	v_mov_b32_e32 v217, v83
	v_mov_b32_e32 v218, v84
	v_mov_b32_e32 v219, v85
	v_mov_b32_e32 v220, v86
	v_mov_b32_e32 v221, v87
	v_mov_b32_e32 v222, v88
	v_mov_b32_e32 v223, v89
	v_mov_b32_e32 v224, v90
	v_mov_b32_e32 v225, v91
	v_mov_b32_e32 v226, v92
	v_mov_b32_e32 v227, v93
	v_mov_b32_e32 v228, v94
	v_mov_b32_e32 v229, v95
	s_branch .Lgu_s_x

; __device__ void phase_gather(const P& p, int vb, int nvb, char* smem) {
;     ...
;     for (int b0 = 0; b0 < 128; b0 += 8) {
.Lgu_s_x:
	s_branch .Lgu_body
